# norm_alow 16-to-1 transposing reduction tree rebuilt with permlane swaps and bank-masked DPP adds (no LDS shuffles, no selects)
# speedup vs baseline: 1.0050x; 1.0015x over previous
; #define LAS __attribute__((address_space(3)))
; __device__ __forceinline__ unsigned cvt_pk_bf16(float lo, float hi) { unsigned r; asm volatile("v_cvt_pk_bf16_f32 %0, %1, %2" : "=v"(r) : "v"(lo), "v"(hi)); return r; }
; __device__ void phase_norm_alow(const Params& P, int l, int half, LAS unsigned char* lds) {
;     ...
;         for (int i = 0; i < 4; ++i) { v[i] = nv[i]; ss += v[i][0] * v[i][0] + v[i][1] * v[i][1] + v[i][2] * v[i][2] + v[i][3] * v[i][3]; }
;         if (row + rstride < TH) {
; #pragma unroll
;             for (int i = 0; i < 4; ++i) nv[i] = *(const f32x4*)(xs + (size_t)(row + rstride) * DM + i * 256 + lane * 4);
;         }
;         ss = wave_sum(ss);
;         const float r = rsqrtf(ss * (1.0f / DM) + EPS);
;         float a[16];
; #pragma unroll
;         for (int c = 0; c < 16; ++c) a[c] = 0.f;
; #pragma unroll
;         for (int i = 0; i < 4; ++i) { f32x4 h = v[i] * r * gv[i];
;             u32x2 w; w.x = cvt_pk_bf16(h[0], h[1]); w.y = cvt_pk_bf16(h[2], h[3]);
;             *(u32x2*)(H + (size_t)row * DM + i * 256 + lane * 4) = w;
; #pragma unroll
;             for (int c = 0; c < 16; ++c) { const f32x4 wv = *(const LAS f32x4*)(WaT + c * 1024 + i * 256 + lane * 4); a[c] += h[0] * wv[0] + h[1] * wv[1] + h[2] * wv[2] + h[3] * wv[3]; } }
.LBB0_120:
	s_or_b64 exec, exec, s[30:31]
	v_mul_f32_e32 v51, v47, v47
	v_mul_f32_e32 v58, v43, v43
	v_fmac_f32_e32 v51, v46, v46
	v_fmac_f32_e32 v58, v42, v42
	v_fmac_f32_e32 v51, v48, v48
	v_fmac_f32_e32 v58, v44, v44
	v_fmac_f32_e32 v51, v49, v49
	v_fmac_f32_e32 v58, v45, v45
	v_add_f32_e32 v51, v51, v58
	v_mul_f32_e32 v58, v39, v39
	v_fmac_f32_e32 v58, v38, v38
	v_fmac_f32_e32 v58, v40, v40
	v_fmac_f32_e32 v58, v41, v41
	v_add_f32_e32 v51, v51, v58
	v_mul_f32_e32 v58, v35, v35
	v_fmac_f32_e32 v58, v34, v34
	v_fmac_f32_e32 v58, v36, v36
	v_fmac_f32_e32 v58, v37, v37
	v_add_f32_e32 v51, v51, v58
	v_mov_b32_e32 v58, v51
	s_nop 1
	v_permlane32_swap_b32_e32 v58, v51
	s_nop 1
	v_lshl_add_u64 v[68:69], s[74:75], 0, v[56:57]
	s_waitcnt lgkmcnt(0)
	v_add_f32_e32 v51, v51, v58
	v_mov_b32_e32 v58, v51
	s_nop 1
	v_permlane16_swap_b32_e32 v58, v51
	s_nop 1
	s_waitcnt lgkmcnt(0)
	v_add_f32_e32 v51, v51, v58
	s_nop 1
	v_mov_b32_dpp v58, v51 row_ror:8 row_mask:0xf bank_mask:0xf
	s_waitcnt lgkmcnt(0)
	v_add_f32_e32 v51, v51, v58
	s_nop 1
	v_mov_b32_dpp v58, v51 row_shl:4 row_mask:0xf bank_mask:0x5
	s_nop 1
	v_mov_b32_dpp v58, v51 row_shr:4 row_mask:0xf bank_mask:0xa
	s_waitcnt lgkmcnt(0)
	v_add_f32_e32 v51, v51, v58
	s_nop 1
	v_mov_b32_dpp v58, v51 quad_perm:[2,3,0,1] row_mask:0xf bank_mask:0xf
	s_waitcnt lgkmcnt(0)
	v_add_f32_e32 v51, v51, v58
	s_nop 1
	v_mov_b32_dpp v58, v51 quad_perm:[1,0,3,2] row_mask:0xf bank_mask:0xf
	s_waitcnt lgkmcnt(0)
	v_add_f32_e32 v51, v51, v58
	v_fmamk_f32 v51, v51, 0x3a800000, v1
	v_cmp_gt_f32_e64 s[0:1], s33, v51
	v_mul_f32_e32 v58, 0x4b800000, v51
	s_nop 0
	v_cndmask_b32_e64 v51, v51, v58, s[0:1]
	v_rsq_f32_e32 v51, v51
	s_nop 0
	v_mul_f32_e32 v58, 0x45800000, v51
	v_cndmask_b32_e64 v58, v51, v58, s[0:1]
	v_pk_mul_f32 v[46:47], v[46:47], v[58:59] op_sel_hi:[1,0]
	s_mov_b32 s0, 0x5a88000
	v_pk_mul_f32 v[48:49], v[48:49], v[58:59] op_sel_hi:[1,0]
	v_pk_mul_f32 v[60:61], v[14:15], v[46:47]
	v_add_co_u32_e64 v46, s[0:1], s0, v68
	v_pk_mul_f32 v[48:49], v[16:17], v[48:49]
	v_cvt_pk_bf16_f32 v70, v60, v61
	s_nop 0
	v_addc_co_u32_e64 v47, s[0:1], 0, v69, s[0:1]
	v_cvt_pk_bf16_f32 v71, v48, v49
	global_store_dwordx2 v[46:47], v[70:71], off
	ds_read_b128 v[100:103], v67
	ds_read_b128 v[104:107], v67 offset:4096
	ds_read_b128 v[108:111], v67 offset:8192
	ds_read_b128 v[112:115], v67 offset:12288
	ds_read_b128 v[116:119], v67 offset:16384
	ds_read_b128 v[120:123], v67 offset:20480
	ds_read_b128 v[124:127], v67 offset:24576
	s_waitcnt lgkmcnt(6)
	v_pk_mul_f32 v[148:149], v[100:101], v[60:61]
	v_pk_fma_f32 v[148:149], v[102:103], v[48:49], v[148:149]
	ds_read_b128 v[128:131], v67 offset:28672
	s_waitcnt lgkmcnt(6)
	v_pk_mul_f32 v[150:151], v[104:105], v[60:61]
	v_pk_fma_f32 v[150:151], v[106:107], v[48:49], v[150:151]
	ds_read_b128 v[100:103], v67 offset:32768
	s_waitcnt lgkmcnt(6)
	v_pk_mul_f32 v[152:153], v[108:109], v[60:61]
	v_pk_fma_f32 v[152:153], v[110:111], v[48:49], v[152:153]
	ds_read_b128 v[104:107], v67 offset:36864
	s_waitcnt lgkmcnt(6)
	v_pk_mul_f32 v[154:155], v[112:113], v[60:61]
	v_pk_fma_f32 v[154:155], v[114:115], v[48:49], v[154:155]
	ds_read_b128 v[108:111], v67 offset:40960
	s_waitcnt lgkmcnt(6)
	v_pk_mul_f32 v[156:157], v[116:117], v[60:61]
	v_pk_fma_f32 v[156:157], v[118:119], v[48:49], v[156:157]
	ds_read_b128 v[112:115], v67 offset:45056
	s_waitcnt lgkmcnt(6)
	v_pk_mul_f32 v[158:159], v[120:121], v[60:61]
	v_pk_fma_f32 v[158:159], v[122:123], v[48:49], v[158:159]
	ds_read_b128 v[116:119], v67 offset:49152
	s_waitcnt lgkmcnt(6)
	v_pk_mul_f32 v[160:161], v[124:125], v[60:61]
	v_pk_fma_f32 v[160:161], v[126:127], v[48:49], v[160:161]
	ds_read_b128 v[120:123], v67 offset:53248
	s_waitcnt lgkmcnt(6)
	v_pk_mul_f32 v[162:163], v[128:129], v[60:61]
	v_pk_fma_f32 v[162:163], v[130:131], v[48:49], v[162:163]
	ds_read_b128 v[124:127], v67 offset:57344
	s_waitcnt lgkmcnt(6)
	v_pk_mul_f32 v[164:165], v[100:101], v[60:61]
	v_pk_fma_f32 v[164:165], v[102:103], v[48:49], v[164:165]
	ds_read_b128 v[128:131], v67 offset:61440
	s_waitcnt lgkmcnt(6)
	v_pk_mul_f32 v[168:169], v[104:105], v[60:61]
	v_pk_fma_f32 v[168:169], v[106:107], v[48:49], v[168:169]
	ds_read_b128 v[100:103], v67 offset:1024
	s_waitcnt lgkmcnt(6)
	v_pk_mul_f32 v[170:171], v[108:109], v[60:61]
	v_pk_fma_f32 v[170:171], v[110:111], v[48:49], v[170:171]
	ds_read_b128 v[104:107], v67 offset:5120
	s_waitcnt lgkmcnt(6)
	v_pk_mul_f32 v[172:173], v[112:113], v[60:61]
	v_pk_fma_f32 v[172:173], v[114:115], v[48:49], v[172:173]
	ds_read_b128 v[108:111], v67 offset:9216
	s_waitcnt lgkmcnt(6)
	v_pk_mul_f32 v[174:175], v[116:117], v[60:61]
	v_pk_fma_f32 v[174:175], v[118:119], v[48:49], v[174:175]
	ds_read_b128 v[112:115], v67 offset:13312
	s_waitcnt lgkmcnt(6)
	v_pk_mul_f32 v[176:177], v[120:121], v[60:61]
	v_pk_fma_f32 v[176:177], v[122:123], v[48:49], v[176:177]
	ds_read_b128 v[116:119], v67 offset:17408
	s_waitcnt lgkmcnt(6)
	v_pk_mul_f32 v[178:179], v[124:125], v[60:61]
	v_pk_fma_f32 v[178:179], v[126:127], v[48:49], v[178:179]
	ds_read_b128 v[120:123], v67 offset:21504
	s_waitcnt lgkmcnt(6)
	v_pk_mul_f32 v[180:181], v[128:129], v[60:61]
	v_pk_fma_f32 v[180:181], v[130:131], v[48:49], v[180:181]
	v_pk_mul_f32 v[60:61], v[42:43], v[58:59] op_sel_hi:[1,0]
	v_pk_mul_f32 v[42:43], v[44:45], v[58:59] op_sel_hi:[1,0]
	v_pk_mul_f32 v[44:45], v[10:11], v[60:61]
	v_pk_mul_f32 v[42:43], v[12:13], v[42:43]
	v_cvt_pk_bf16_f32 v60, v44, v45
	s_nop 0
	v_cvt_pk_bf16_f32 v61, v42, v43
	ds_read_b128 v[124:127], v67 offset:25600
	global_store_dwordx2 v[46:47], v[60:61], off offset:512
	s_waitcnt lgkmcnt(6)
; #define LAS __attribute__((address_space(3)))
; __device__ __forceinline__ unsigned cvt_pk_bf16(float lo, float hi) { unsigned r; asm volatile("v_cvt_pk_bf16_f32 %0, %1, %2" : "=v"(r) : "v"(lo), "v"(hi)); return r; }
; __device__ void phase_norm_alow(const Params& P, int l, int half, LAS unsigned char* lds) {
;     ...
;         for (int i = 0; i < 4; ++i) { f32x4 h = v[i] * r * gv[i];
;             u32x2 w; w.x = cvt_pk_bf16(h[0], h[1]); w.y = cvt_pk_bf16(h[2], h[3]);
;             *(u32x2*)(H + (size_t)row * DM + i * 256 + lane * 4) = w;
; #pragma unroll
;             for (int c = 0; c < 16; ++c) { const f32x4 wv = *(const LAS f32x4*)(WaT + c * 1024 + i * 256 + lane * 4); a[c] += h[0] * wv[0] + h[1] * wv[1] + h[2] * wv[2] + h[3] * wv[3]; } }
	v_pk_fma_f32 v[148:149], v[100:101], v[44:45], v[148:149]
	v_pk_fma_f32 v[148:149], v[102:103], v[42:43], v[148:149]
	ds_read_b128 v[128:131], v67 offset:29696
	s_waitcnt lgkmcnt(6)
	v_pk_fma_f32 v[150:151], v[104:105], v[44:45], v[150:151]
	v_pk_fma_f32 v[150:151], v[106:107], v[42:43], v[150:151]
	ds_read_b128 v[100:103], v67 offset:33792
	s_waitcnt lgkmcnt(6)
	v_pk_fma_f32 v[152:153], v[108:109], v[44:45], v[152:153]
	v_pk_fma_f32 v[152:153], v[110:111], v[42:43], v[152:153]
	ds_read_b128 v[104:107], v67 offset:37888
	s_waitcnt lgkmcnt(6)
	v_pk_fma_f32 v[154:155], v[112:113], v[44:45], v[154:155]
	v_pk_fma_f32 v[154:155], v[114:115], v[42:43], v[154:155]
	ds_read_b128 v[108:111], v67 offset:41984
	s_waitcnt lgkmcnt(6)
	v_pk_fma_f32 v[156:157], v[116:117], v[44:45], v[156:157]
	v_pk_fma_f32 v[156:157], v[118:119], v[42:43], v[156:157]
	ds_read_b128 v[112:115], v67 offset:46080
	s_waitcnt lgkmcnt(6)
	v_pk_fma_f32 v[158:159], v[120:121], v[44:45], v[158:159]
	v_pk_fma_f32 v[158:159], v[122:123], v[42:43], v[158:159]
	ds_read_b128 v[116:119], v67 offset:50176
	s_waitcnt lgkmcnt(6)
	v_pk_fma_f32 v[160:161], v[124:125], v[44:45], v[160:161]
	v_pk_fma_f32 v[160:161], v[126:127], v[42:43], v[160:161]
	ds_read_b128 v[120:123], v67 offset:54272
	s_waitcnt lgkmcnt(6)
	v_pk_fma_f32 v[162:163], v[128:129], v[44:45], v[162:163]
	v_pk_fma_f32 v[162:163], v[130:131], v[42:43], v[162:163]
	ds_read_b128 v[124:127], v67 offset:58368
	s_waitcnt lgkmcnt(6)
	v_pk_fma_f32 v[164:165], v[100:101], v[44:45], v[164:165]
	v_pk_fma_f32 v[164:165], v[102:103], v[42:43], v[164:165]
	ds_read_b128 v[128:131], v67 offset:62464
	s_waitcnt lgkmcnt(6)
	v_pk_fma_f32 v[168:169], v[104:105], v[44:45], v[168:169]
	v_pk_fma_f32 v[168:169], v[106:107], v[42:43], v[168:169]
	ds_read_b128 v[100:103], v67 offset:2048
	s_waitcnt lgkmcnt(6)
	v_pk_fma_f32 v[170:171], v[108:109], v[44:45], v[170:171]
	v_pk_fma_f32 v[170:171], v[110:111], v[42:43], v[170:171]
	ds_read_b128 v[104:107], v67 offset:6144
	s_waitcnt lgkmcnt(6)
	v_pk_fma_f32 v[172:173], v[112:113], v[44:45], v[172:173]
	v_pk_fma_f32 v[172:173], v[114:115], v[42:43], v[172:173]
	ds_read_b128 v[108:111], v67 offset:10240
	s_waitcnt lgkmcnt(6)
	v_pk_fma_f32 v[174:175], v[116:117], v[44:45], v[174:175]
	v_pk_fma_f32 v[174:175], v[118:119], v[42:43], v[174:175]
	ds_read_b128 v[112:115], v67 offset:14336
	s_waitcnt lgkmcnt(6)
	v_pk_fma_f32 v[176:177], v[120:121], v[44:45], v[176:177]
	v_pk_fma_f32 v[176:177], v[122:123], v[42:43], v[176:177]
	ds_read_b128 v[116:119], v67 offset:18432
	s_waitcnt lgkmcnt(6)
	v_pk_fma_f32 v[178:179], v[124:125], v[44:45], v[178:179]
	v_pk_fma_f32 v[178:179], v[126:127], v[42:43], v[178:179]
	ds_read_b128 v[120:123], v67 offset:22528
	s_waitcnt lgkmcnt(6)
	v_pk_fma_f32 v[180:181], v[128:129], v[44:45], v[180:181]
	v_pk_fma_f32 v[180:181], v[130:131], v[42:43], v[180:181]
	v_pk_mul_f32 v[42:43], v[38:39], v[58:59] op_sel_hi:[1,0]
	v_pk_mul_f32 v[38:39], v[40:41], v[58:59] op_sel_hi:[1,0]
	v_pk_mul_f32 v[40:41], v[6:7], v[42:43]
	v_pk_mul_f32 v[38:39], v[8:9], v[38:39]
	v_cvt_pk_bf16_f32 v42, v40, v41
	v_cvt_pk_bf16_f32 v43, v38, v39
	global_store_dwordx2 v[46:47], v[42:43], off offset:1024
	ds_read_b128 v[124:127], v67 offset:26624
	ds_read_b128 v[128:131], v67 offset:30720
	s_waitcnt lgkmcnt(7)
	v_pk_fma_f32 v[148:149], v[100:101], v[40:41], v[148:149]
	v_pk_fma_f32 v[148:149], v[102:103], v[38:39], v[148:149]
	s_waitcnt lgkmcnt(6)
	v_pk_fma_f32 v[150:151], v[104:105], v[40:41], v[150:151]
	v_pk_fma_f32 v[150:151], v[106:107], v[38:39], v[150:151]
	ds_read_b128 v[100:103], v67 offset:34816
	s_waitcnt lgkmcnt(6)
	v_pk_fma_f32 v[152:153], v[108:109], v[40:41], v[152:153]
	v_pk_fma_f32 v[152:153], v[110:111], v[38:39], v[152:153]
	ds_read_b128 v[104:107], v67 offset:38912
	s_waitcnt lgkmcnt(6)
	v_pk_fma_f32 v[154:155], v[112:113], v[40:41], v[154:155]
	v_pk_fma_f32 v[154:155], v[114:115], v[38:39], v[154:155]
	ds_read_b128 v[108:111], v67 offset:43008
	s_waitcnt lgkmcnt(6)
	v_pk_fma_f32 v[156:157], v[116:117], v[40:41], v[156:157]
	v_pk_fma_f32 v[156:157], v[118:119], v[38:39], v[156:157]
	ds_read_b128 v[112:115], v67 offset:47104
	s_waitcnt lgkmcnt(6)
	v_pk_fma_f32 v[158:159], v[120:121], v[40:41], v[158:159]
	v_pk_fma_f32 v[158:159], v[122:123], v[38:39], v[158:159]
	ds_read_b128 v[116:119], v67 offset:51200
	s_waitcnt lgkmcnt(6)
	v_pk_fma_f32 v[160:161], v[124:125], v[40:41], v[160:161]
	v_pk_fma_f32 v[160:161], v[126:127], v[38:39], v[160:161]
	ds_read_b128 v[120:123], v67 offset:55296
	s_waitcnt lgkmcnt(6)
	v_pk_fma_f32 v[162:163], v[128:129], v[40:41], v[162:163]
	v_pk_fma_f32 v[162:163], v[130:131], v[38:39], v[162:163]
	ds_read_b128 v[124:127], v67 offset:59392
	s_waitcnt lgkmcnt(6)
	v_pk_fma_f32 v[164:165], v[100:101], v[40:41], v[164:165]
	v_pk_fma_f32 v[164:165], v[102:103], v[38:39], v[164:165]
	ds_read_b128 v[128:131], v67 offset:63488
	s_waitcnt lgkmcnt(6)
	v_pk_fma_f32 v[168:169], v[104:105], v[40:41], v[168:169]
	v_pk_fma_f32 v[168:169], v[106:107], v[38:39], v[168:169]
	ds_read_b128 v[100:103], v67 offset:3072
	s_waitcnt lgkmcnt(6)
	v_pk_fma_f32 v[170:171], v[108:109], v[40:41], v[170:171]
	v_pk_fma_f32 v[170:171], v[110:111], v[38:39], v[170:171]
	ds_read_b128 v[104:107], v67 offset:7168
	s_waitcnt lgkmcnt(6)
	v_pk_fma_f32 v[172:173], v[112:113], v[40:41], v[172:173]
	v_pk_fma_f32 v[172:173], v[114:115], v[38:39], v[172:173]
	ds_read_b128 v[108:111], v67 offset:11264
	s_waitcnt lgkmcnt(6)
	v_pk_fma_f32 v[174:175], v[116:117], v[40:41], v[174:175]
	v_pk_fma_f32 v[174:175], v[118:119], v[38:39], v[174:175]
	ds_read_b128 v[112:115], v67 offset:15360
	s_waitcnt lgkmcnt(6)
; #define LAS __attribute__((address_space(3)))
; __device__ __forceinline__ unsigned cvt_pk_bf16(float lo, float hi) { unsigned r; asm volatile("v_cvt_pk_bf16_f32 %0, %1, %2" : "=v"(r) : "v"(lo), "v"(hi)); return r; }
; __device__ void phase_norm_alow(const Params& P, int l, int half, LAS unsigned char* lds) {
;     ...
;         for (int i = 0; i < 4; ++i) { f32x4 h = v[i] * r * gv[i];
;             u32x2 w; w.x = cvt_pk_bf16(h[0], h[1]); w.y = cvt_pk_bf16(h[2], h[3]);
;             *(u32x2*)(H + (size_t)row * DM + i * 256 + lane * 4) = w;
; #pragma unroll
;             for (int c = 0; c < 16; ++c) { const f32x4 wv = *(const LAS f32x4*)(WaT + c * 1024 + i * 256 + lane * 4); a[c] += h[0] * wv[0] + h[1] * wv[1] + h[2] * wv[2] + h[3] * wv[3]; } }
;         float b8[8], b4[4], b2[2], b1;
;         { const bool up = (lane & 32) != 0;
; #pragma unroll
;           for (int c = 0; c < 8; ++c) { const float keep = up ? a[c + 8] : a[c], send = up ? a[c] : a[c + 8]; b8[c] = keep + __shfl_xor(send, 32); } }
;         { const bool up = (lane & 16) != 0;
; #pragma unroll
;           for (int c = 0; c < 4; ++c) { const float keep = up ? b8[c + 4] : b8[c], send = up ? b8[c] : b8[c + 4]; b4[c] = keep + __shfl_xor(send, 16); } }
;         { const bool up = (lane & 8) != 0;
; #pragma unroll
;           for (int c = 0; c < 2; ++c) { const float keep = up ? b4[c + 2] : b4[c], send = up ? b4[c] : b4[c + 2]; b2[c] = keep + __shfl_xor(send, 8); } }
;         { const bool up = (lane & 4) != 0; const float keep = up ? b2[1] : b2[0], send = up ? b2[0] : b2[1]; b1 = keep + __shfl_xor(send, 4); }
;         b1 += __shfl_xor(b1, 2); b1 += __shfl_xor(b1, 1);
;         if ((lane & 3) == 0) { const int co = ((lane >> 5) & 1) * 8 + ((lane >> 4) & 1) * 4 + ((lane >> 3) & 1) * 2 + ((lane >> 2) & 1); AL[(size_t)row * 16 + co] = b1; }
	v_pk_fma_f32 v[176:177], v[120:121], v[40:41], v[176:177]
	v_pk_fma_f32 v[176:177], v[122:123], v[38:39], v[176:177]
	ds_read_b128 v[116:119], v67 offset:19456
	s_waitcnt lgkmcnt(6)
	v_pk_fma_f32 v[178:179], v[124:125], v[40:41], v[178:179]
	v_pk_fma_f32 v[178:179], v[126:127], v[38:39], v[178:179]
	ds_read_b128 v[120:123], v67 offset:23552
	s_waitcnt lgkmcnt(6)
	v_pk_fma_f32 v[180:181], v[128:129], v[40:41], v[180:181]
	v_pk_fma_f32 v[180:181], v[130:131], v[38:39], v[180:181]
	v_pk_mul_f32 v[40:41], v[34:35], v[58:59] op_sel_hi:[1,0]
	v_pk_mul_f32 v[34:35], v[36:37], v[58:59] op_sel_hi:[1,0]
	v_pk_mul_f32 v[36:37], v[2:3], v[40:41]
	v_pk_mul_f32 v[34:35], v[4:5], v[34:35]
	v_cvt_pk_bf16_f32 v40, v36, v37
	s_nop 0
	v_cvt_pk_bf16_f32 v41, v34, v35
	ds_read_b128 v[124:127], v67 offset:27648
	global_store_dwordx2 v[46:47], v[40:41], off offset:1536
	s_waitcnt lgkmcnt(6)
	v_pk_fma_f32 v[148:149], v[100:101], v[36:37], v[148:149]
	v_pk_fma_f32 v[148:149], v[102:103], v[34:35], v[148:149]
	ds_read_b128 v[128:131], v67 offset:31744
	v_add_f32_e32 v39, v148, v149
	s_waitcnt lgkmcnt(6)
	v_pk_fma_f32 v[150:151], v[104:105], v[36:37], v[150:151]
	v_pk_fma_f32 v[150:151], v[106:107], v[34:35], v[150:151]
	ds_read_b128 v[100:103], v67 offset:35840
	v_add_f32_e32 v40, v150, v151
	s_waitcnt lgkmcnt(6)
	v_pk_fma_f32 v[152:153], v[108:109], v[36:37], v[152:153]
	v_pk_fma_f32 v[152:153], v[110:111], v[34:35], v[152:153]
	ds_read_b128 v[104:107], v67 offset:39936
	v_add_f32_e32 v41, v152, v153
	s_waitcnt lgkmcnt(6)
	v_pk_fma_f32 v[154:155], v[112:113], v[36:37], v[154:155]
	v_pk_fma_f32 v[154:155], v[114:115], v[34:35], v[154:155]
	v_add_f32_e32 v42, v154, v155
	ds_read_b128 v[108:111], v67 offset:44032
	s_waitcnt lgkmcnt(6)
	v_pk_fma_f32 v[156:157], v[116:117], v[36:37], v[156:157]
	v_pk_fma_f32 v[156:157], v[118:119], v[34:35], v[156:157]
	ds_read_b128 v[112:115], v67 offset:48128
	v_add_f32_e32 v43, v156, v157
	s_waitcnt lgkmcnt(6)
	v_pk_fma_f32 v[158:159], v[120:121], v[36:37], v[158:159]
	v_pk_fma_f32 v[158:159], v[122:123], v[34:35], v[158:159]
	v_add_f32_e32 v48, v158, v159
	ds_read_b128 v[116:119], v67 offset:52224
	s_waitcnt lgkmcnt(6)
	v_pk_fma_f32 v[160:161], v[124:125], v[36:37], v[160:161]
	v_pk_fma_f32 v[160:161], v[126:127], v[34:35], v[160:161]
	v_add_f32_e32 v49, v160, v161
	ds_read_b128 v[120:123], v67 offset:56320
	s_waitcnt lgkmcnt(6)
	v_pk_fma_f32 v[162:163], v[128:129], v[36:37], v[162:163]
	v_pk_fma_f32 v[162:163], v[130:131], v[34:35], v[162:163]
	v_add_f32_e32 v51, v162, v163
	ds_read_b128 v[124:127], v67 offset:60416
	s_waitcnt lgkmcnt(6)
	v_pk_fma_f32 v[164:165], v[100:101], v[36:37], v[164:165]
	v_pk_fma_f32 v[164:165], v[102:103], v[34:35], v[164:165]
	v_add_f32_e32 v58, v164, v165
	ds_read_b128 v[128:131], v67 offset:64512
	s_waitcnt lgkmcnt(6)
	v_pk_fma_f32 v[168:169], v[104:105], v[36:37], v[168:169]
	v_pk_fma_f32 v[168:169], v[106:107], v[34:35], v[168:169]
	v_add_f32_e32 v60, v168, v169
	s_waitcnt lgkmcnt(5)
	v_pk_fma_f32 v[170:171], v[108:109], v[36:37], v[170:171]
	v_pk_fma_f32 v[170:171], v[110:111], v[34:35], v[170:171]
	v_add_f32_e32 v61, v170, v171
	s_waitcnt lgkmcnt(4)
	v_pk_fma_f32 v[172:173], v[112:113], v[36:37], v[172:173]
	v_pk_fma_f32 v[172:173], v[114:115], v[34:35], v[172:173]
	v_add_f32_e32 v68, v172, v173
	s_waitcnt lgkmcnt(3)
	v_pk_fma_f32 v[174:175], v[116:117], v[36:37], v[174:175]
	v_pk_fma_f32 v[174:175], v[118:119], v[34:35], v[174:175]
	v_add_f32_e32 v69, v174, v175
	s_waitcnt lgkmcnt(2)
	v_pk_fma_f32 v[176:177], v[120:121], v[36:37], v[176:177]
	v_pk_fma_f32 v[176:177], v[122:123], v[34:35], v[176:177]
	v_add_f32_e32 v70, v176, v177
	s_waitcnt lgkmcnt(1)
	v_pk_fma_f32 v[178:179], v[124:125], v[36:37], v[178:179]
	v_pk_fma_f32 v[178:179], v[126:127], v[34:35], v[178:179]
	v_add_f32_e32 v71, v178, v179
	s_waitcnt lgkmcnt(0)
	v_pk_fma_f32 v[180:181], v[128:129], v[36:37], v[180:181]
	v_pk_fma_f32 v[180:181], v[130:131], v[34:35], v[180:181]
	v_add_f32_e32 v34, v180, v181
	s_waitcnt lgkmcnt(2)
	s_waitcnt lgkmcnt(2)
	s_waitcnt lgkmcnt(2)
	s_waitcnt lgkmcnt(3)
	s_waitcnt lgkmcnt(2)
	s_waitcnt lgkmcnt(1)
	s_waitcnt lgkmcnt(0)
	s_waitcnt lgkmcnt(0)
	s_waitcnt lgkmcnt(1)
	s_waitcnt lgkmcnt(1)
	s_waitcnt lgkmcnt(0)
	s_waitcnt lgkmcnt(1)
	s_waitcnt lgkmcnt(1)
	s_waitcnt lgkmcnt(0)
	s_waitcnt lgkmcnt(0)
	s_nop 1
	v_permlane32_swap_b32_e32 v39, v58
	s_nop 1
	v_add_f32_e32 v39, v39, v58
	s_nop 1
	v_permlane32_swap_b32_e32 v40, v60
	s_nop 1
	v_add_f32_e32 v40, v40, v60
	s_nop 1
	v_permlane32_swap_b32_e32 v41, v61
	s_nop 1
	v_add_f32_e32 v41, v41, v61
	s_nop 1
	v_permlane32_swap_b32_e32 v42, v68
	s_nop 1
	v_add_f32_e32 v42, v42, v68
	s_nop 1
	v_permlane32_swap_b32_e32 v43, v69
	s_nop 1
	v_add_f32_e32 v43, v43, v69
	s_nop 1
	v_permlane32_swap_b32_e32 v48, v70
	s_nop 1
	v_add_f32_e32 v48, v48, v70
	s_nop 1
	v_permlane32_swap_b32_e32 v49, v71
	s_nop 1
	v_add_f32_e32 v49, v49, v71
	s_nop 1
	v_permlane32_swap_b32_e32 v51, v34
	s_nop 1
	v_add_f32_e32 v51, v51, v34
	s_nop 1
	v_permlane16_swap_b32_e32 v40, v48
	s_nop 1
	v_add_f32_e32 v40, v40, v48
	s_nop 1
	v_permlane16_swap_b32_e32 v39, v43
	s_nop 1
	v_add_f32_e32 v39, v39, v43
	s_nop 1
	v_permlane16_swap_b32_e32 v41, v49
	s_nop 1
	v_add_f32_e32 v41, v41, v49
	s_nop 1
	v_permlane16_swap_b32_e32 v42, v51
	s_nop 1
	v_add_f32_e32 v42, v42, v51
	s_nop 1
	v_add_f32_dpp v39, v39, v39 row_ror:8 row_mask:0xf bank_mask:0x3
	s_nop 1
	v_add_f32_dpp v39, v41, v41 row_ror:8 row_mask:0xf bank_mask:0xc
	s_nop 1
	v_add_f32_dpp v40, v40, v40 row_ror:8 row_mask:0xf bank_mask:0x3
	s_nop 1
	v_add_f32_dpp v40, v42, v42 row_ror:8 row_mask:0xf bank_mask:0xc
	s_nop 1
	v_add_f32_dpp v39, v39, v39 row_shl:4 row_mask:0xf bank_mask:0x5
	s_nop 1
	v_add_f32_dpp v39, v40, v40 row_shr:4 row_mask:0xf bank_mask:0xa
	v_mov_b32_e32 v34, v39
	s_nop 0
	s_nop 1
	v_mov_b32_dpp v35, v34 quad_perm:[2,3,0,1] row_mask:0xf bank_mask:0xf
	s_waitcnt lgkmcnt(0)
	v_add_f32_e32 v34, v34, v35
	s_nop 1
	v_mov_b32_dpp v35, v34 quad_perm:[1,0,3,2] row_mask:0xf bank_mask:0xf
	s_and_saveexec_b64 s[0:1], s[42:43]
	s_cbranch_execz .LBB0_117
	v_lshl_add_u64 v[36:37], s[74:75], 0, v[54:55]
	s_waitcnt lgkmcnt(0)
	v_add_f32_e32 v34, v34, v35
	global_store_dword v[36:37], v34, off
	s_branch .LBB0_117

; #define LAS __attribute__((address_space(3)))
; __device__ __forceinline__ unsigned cvt_pk_bf16(float lo, float hi) { unsigned r; asm volatile("v_cvt_pk_bf16_f32 %0, %1, %2" : "=v"(r) : "v"(lo), "v"(hi)); return r; }
; __device__ void phase_norm_alow(const Params& P, int l, int half, LAS unsigned char* lds) {
;     ...
;         for (int i = 0; i < 4; ++i) { v[i] = nv[i]; ss += v[i][0] * v[i][0] + v[i][1] * v[i][1] + v[i][2] * v[i][2] + v[i][3] * v[i][3]; }
;         if (row + rstride < TH) {
; #pragma unroll
;             for (int i = 0; i < 4; ++i) nv[i] = *(const f32x4*)(xs + (size_t)(row + rstride) * DM + i * 256 + lane * 4);
;         }
;         ss = wave_sum(ss);
;         const float r = rsqrtf(ss * (1.0f / DM) + EPS);
;         float a[16];
; #pragma unroll
;         for (int c = 0; c < 16; ++c) a[c] = 0.f;
; #pragma unroll
;         for (int i = 0; i < 4; ++i) { f32x4 h = v[i] * r * gv[i];
;             u32x2 w; w.x = cvt_pk_bf16(h[0], h[1]); w.y = cvt_pk_bf16(h[2], h[3]);
;             *(u32x2*)(H + (size_t)row * DM + i * 256 + lane * 4) = w;
; #pragma unroll
;             for (int c = 0; c < 16; ++c) { const f32x4 wv = *(const LAS f32x4*)(WaT + c * 1024 + i * 256 + lane * 4); a[c] += h[0] * wv[0] + h[1] * wv[1] + h[2] * wv[2] + h[3] * wv[3]; } }
.LBB0_242:
	s_or_b64 exec, exec, s[30:31]
	v_mul_f32_e32 v51, v47, v47
	v_mul_f32_e32 v58, v43, v43
	v_fmac_f32_e32 v51, v46, v46
	v_fmac_f32_e32 v58, v42, v42
	v_fmac_f32_e32 v51, v48, v48
	v_fmac_f32_e32 v58, v44, v44
	v_fmac_f32_e32 v51, v49, v49
	v_fmac_f32_e32 v58, v45, v45
	v_add_f32_e32 v51, v51, v58
	v_mul_f32_e32 v58, v39, v39
	v_fmac_f32_e32 v58, v38, v38
	v_fmac_f32_e32 v58, v40, v40
	v_fmac_f32_e32 v58, v41, v41
	v_add_f32_e32 v51, v51, v58
	v_mul_f32_e32 v58, v35, v35
	v_fmac_f32_e32 v58, v34, v34
	v_fmac_f32_e32 v58, v36, v36
	v_fmac_f32_e32 v58, v37, v37
	v_add_f32_e32 v51, v51, v58
	v_mov_b32_e32 v58, v51
	s_nop 1
	v_permlane32_swap_b32_e32 v58, v51
	s_nop 1
	v_lshl_add_u64 v[68:69], s[74:75], 0, v[54:55]
	s_waitcnt lgkmcnt(0)
	v_add_f32_e32 v51, v51, v58
	v_mov_b32_e32 v58, v51
	s_nop 1
	v_permlane16_swap_b32_e32 v58, v51
	s_nop 1
	s_waitcnt lgkmcnt(0)
	v_add_f32_e32 v51, v51, v58
	s_nop 1
	v_mov_b32_dpp v58, v51 row_ror:8 row_mask:0xf bank_mask:0xf
	s_waitcnt lgkmcnt(0)
	v_add_f32_e32 v51, v51, v58
	s_nop 1
	v_mov_b32_dpp v58, v51 row_shl:4 row_mask:0xf bank_mask:0x5
	s_nop 1
	v_mov_b32_dpp v58, v51 row_shr:4 row_mask:0xf bank_mask:0xa
	s_waitcnt lgkmcnt(0)
	v_add_f32_e32 v51, v51, v58
	s_nop 1
	v_mov_b32_dpp v58, v51 quad_perm:[2,3,0,1] row_mask:0xf bank_mask:0xf
	s_waitcnt lgkmcnt(0)
	v_add_f32_e32 v51, v51, v58
	s_nop 1
	v_mov_b32_dpp v58, v51 quad_perm:[1,0,3,2] row_mask:0xf bank_mask:0xf
	s_waitcnt lgkmcnt(0)
	v_add_f32_e32 v51, v51, v58
	v_fmamk_f32 v51, v51, 0x3a800000, v1
	v_cmp_gt_f32_e64 s[0:1], s33, v51
	v_mul_f32_e32 v58, 0x4b800000, v51
	s_nop 0
	v_cndmask_b32_e64 v51, v51, v58, s[0:1]
	v_rsq_f32_e32 v51, v51
	s_nop 0
	v_mul_f32_e32 v58, 0x45800000, v51
	v_cndmask_b32_e64 v58, v51, v58, s[0:1]
	v_pk_mul_f32 v[46:47], v[46:47], v[58:59] op_sel_hi:[1,0]
	s_mov_b32 s0, 0x5a88000
	v_pk_mul_f32 v[48:49], v[48:49], v[58:59] op_sel_hi:[1,0]
	v_pk_mul_f32 v[60:61], v[14:15], v[46:47]
	v_add_co_u32_e64 v46, s[0:1], s0, v68
	v_pk_mul_f32 v[48:49], v[16:17], v[48:49]
	v_cvt_pk_bf16_f32 v70, v60, v61
	s_nop 0
	v_addc_co_u32_e64 v47, s[0:1], 0, v69, s[0:1]
	v_cvt_pk_bf16_f32 v71, v48, v49
	global_store_dwordx2 v[46:47], v[70:71], off
	ds_read_b128 v[100:103], v67
	ds_read_b128 v[104:107], v67 offset:4096
	ds_read_b128 v[108:111], v67 offset:8192
	ds_read_b128 v[112:115], v67 offset:12288
	ds_read_b128 v[116:119], v67 offset:16384
	ds_read_b128 v[120:123], v67 offset:20480
	ds_read_b128 v[124:127], v67 offset:24576
	s_waitcnt lgkmcnt(6)
	v_pk_mul_f32 v[148:149], v[100:101], v[60:61]
	v_pk_fma_f32 v[148:149], v[102:103], v[48:49], v[148:149]
	ds_read_b128 v[128:131], v67 offset:28672
	s_waitcnt lgkmcnt(6)
	v_pk_mul_f32 v[150:151], v[104:105], v[60:61]
	v_pk_fma_f32 v[150:151], v[106:107], v[48:49], v[150:151]
	ds_read_b128 v[100:103], v67 offset:32768
	s_waitcnt lgkmcnt(6)
	v_pk_mul_f32 v[152:153], v[108:109], v[60:61]
	v_pk_fma_f32 v[152:153], v[110:111], v[48:49], v[152:153]
	ds_read_b128 v[104:107], v67 offset:36864
	s_waitcnt lgkmcnt(6)
	v_pk_mul_f32 v[154:155], v[112:113], v[60:61]
	v_pk_fma_f32 v[154:155], v[114:115], v[48:49], v[154:155]
	ds_read_b128 v[108:111], v67 offset:40960
	s_waitcnt lgkmcnt(6)
	v_pk_mul_f32 v[156:157], v[116:117], v[60:61]
	v_pk_fma_f32 v[156:157], v[118:119], v[48:49], v[156:157]
	ds_read_b128 v[112:115], v67 offset:45056
	s_waitcnt lgkmcnt(6)
	v_pk_mul_f32 v[158:159], v[120:121], v[60:61]
	v_pk_fma_f32 v[158:159], v[122:123], v[48:49], v[158:159]
	ds_read_b128 v[116:119], v67 offset:49152
	s_waitcnt lgkmcnt(6)
	v_pk_mul_f32 v[160:161], v[124:125], v[60:61]
	v_pk_fma_f32 v[160:161], v[126:127], v[48:49], v[160:161]
	ds_read_b128 v[120:123], v67 offset:53248
	s_waitcnt lgkmcnt(6)
	v_pk_mul_f32 v[162:163], v[128:129], v[60:61]
	v_pk_fma_f32 v[162:163], v[130:131], v[48:49], v[162:163]
	ds_read_b128 v[124:127], v67 offset:57344
	s_waitcnt lgkmcnt(6)
	v_pk_mul_f32 v[164:165], v[100:101], v[60:61]
	v_pk_fma_f32 v[164:165], v[102:103], v[48:49], v[164:165]
	ds_read_b128 v[128:131], v67 offset:61440
	s_waitcnt lgkmcnt(6)
	v_pk_mul_f32 v[168:169], v[104:105], v[60:61]
	v_pk_fma_f32 v[168:169], v[106:107], v[48:49], v[168:169]
	ds_read_b128 v[100:103], v67 offset:1024
	s_waitcnt lgkmcnt(6)
	v_pk_mul_f32 v[170:171], v[108:109], v[60:61]
	v_pk_fma_f32 v[170:171], v[110:111], v[48:49], v[170:171]
	ds_read_b128 v[104:107], v67 offset:5120
	s_waitcnt lgkmcnt(6)
	v_pk_mul_f32 v[172:173], v[112:113], v[60:61]
	v_pk_fma_f32 v[172:173], v[114:115], v[48:49], v[172:173]
	ds_read_b128 v[108:111], v67 offset:9216
	s_waitcnt lgkmcnt(6)
	v_pk_mul_f32 v[174:175], v[116:117], v[60:61]
	v_pk_fma_f32 v[174:175], v[118:119], v[48:49], v[174:175]
	ds_read_b128 v[112:115], v67 offset:13312
	s_waitcnt lgkmcnt(6)
	v_pk_mul_f32 v[176:177], v[120:121], v[60:61]
	v_pk_fma_f32 v[176:177], v[122:123], v[48:49], v[176:177]
	ds_read_b128 v[116:119], v67 offset:17408
	s_waitcnt lgkmcnt(6)
	v_pk_mul_f32 v[178:179], v[124:125], v[60:61]
	v_pk_fma_f32 v[178:179], v[126:127], v[48:49], v[178:179]
	ds_read_b128 v[120:123], v67 offset:21504
	s_waitcnt lgkmcnt(6)
	v_pk_mul_f32 v[180:181], v[128:129], v[60:61]
	v_pk_fma_f32 v[180:181], v[130:131], v[48:49], v[180:181]
	v_pk_mul_f32 v[60:61], v[42:43], v[58:59] op_sel_hi:[1,0]
	v_pk_mul_f32 v[42:43], v[44:45], v[58:59] op_sel_hi:[1,0]
	v_pk_mul_f32 v[44:45], v[10:11], v[60:61]
	v_pk_mul_f32 v[42:43], v[12:13], v[42:43]
	v_cvt_pk_bf16_f32 v60, v44, v45
	s_nop 0
	v_cvt_pk_bf16_f32 v61, v42, v43
	ds_read_b128 v[124:127], v67 offset:25600
	global_store_dwordx2 v[46:47], v[60:61], off offset:512
	s_waitcnt lgkmcnt(6)
; #define LAS __attribute__((address_space(3)))
; __device__ __forceinline__ unsigned cvt_pk_bf16(float lo, float hi) { unsigned r; asm volatile("v_cvt_pk_bf16_f32 %0, %1, %2" : "=v"(r) : "v"(lo), "v"(hi)); return r; }
; __device__ void phase_norm_alow(const Params& P, int l, int half, LAS unsigned char* lds) {
;     ...
;         for (int i = 0; i < 4; ++i) { f32x4 h = v[i] * r * gv[i];
;             u32x2 w; w.x = cvt_pk_bf16(h[0], h[1]); w.y = cvt_pk_bf16(h[2], h[3]);
;             *(u32x2*)(H + (size_t)row * DM + i * 256 + lane * 4) = w;
; #pragma unroll
;             for (int c = 0; c < 16; ++c) { const f32x4 wv = *(const LAS f32x4*)(WaT + c * 1024 + i * 256 + lane * 4); a[c] += h[0] * wv[0] + h[1] * wv[1] + h[2] * wv[2] + h[3] * wv[3]; } }
	v_pk_fma_f32 v[148:149], v[100:101], v[44:45], v[148:149]
	v_pk_fma_f32 v[148:149], v[102:103], v[42:43], v[148:149]
	ds_read_b128 v[128:131], v67 offset:29696
	s_waitcnt lgkmcnt(6)
	v_pk_fma_f32 v[150:151], v[104:105], v[44:45], v[150:151]
	v_pk_fma_f32 v[150:151], v[106:107], v[42:43], v[150:151]
	ds_read_b128 v[100:103], v67 offset:33792
	s_waitcnt lgkmcnt(6)
	v_pk_fma_f32 v[152:153], v[108:109], v[44:45], v[152:153]
	v_pk_fma_f32 v[152:153], v[110:111], v[42:43], v[152:153]
	ds_read_b128 v[104:107], v67 offset:37888
	s_waitcnt lgkmcnt(6)
	v_pk_fma_f32 v[154:155], v[112:113], v[44:45], v[154:155]
	v_pk_fma_f32 v[154:155], v[114:115], v[42:43], v[154:155]
	ds_read_b128 v[108:111], v67 offset:41984
	s_waitcnt lgkmcnt(6)
	v_pk_fma_f32 v[156:157], v[116:117], v[44:45], v[156:157]
	v_pk_fma_f32 v[156:157], v[118:119], v[42:43], v[156:157]
	ds_read_b128 v[112:115], v67 offset:46080
	s_waitcnt lgkmcnt(6)
	v_pk_fma_f32 v[158:159], v[120:121], v[44:45], v[158:159]
	v_pk_fma_f32 v[158:159], v[122:123], v[42:43], v[158:159]
	ds_read_b128 v[116:119], v67 offset:50176
	s_waitcnt lgkmcnt(6)
	v_pk_fma_f32 v[160:161], v[124:125], v[44:45], v[160:161]
	v_pk_fma_f32 v[160:161], v[126:127], v[42:43], v[160:161]
	ds_read_b128 v[120:123], v67 offset:54272
	s_waitcnt lgkmcnt(6)
	v_pk_fma_f32 v[162:163], v[128:129], v[44:45], v[162:163]
	v_pk_fma_f32 v[162:163], v[130:131], v[42:43], v[162:163]
	ds_read_b128 v[124:127], v67 offset:58368
	s_waitcnt lgkmcnt(6)
	v_pk_fma_f32 v[164:165], v[100:101], v[44:45], v[164:165]
	v_pk_fma_f32 v[164:165], v[102:103], v[42:43], v[164:165]
	ds_read_b128 v[128:131], v67 offset:62464
	s_waitcnt lgkmcnt(6)
	v_pk_fma_f32 v[168:169], v[104:105], v[44:45], v[168:169]
	v_pk_fma_f32 v[168:169], v[106:107], v[42:43], v[168:169]
	ds_read_b128 v[100:103], v67 offset:2048
	s_waitcnt lgkmcnt(6)
	v_pk_fma_f32 v[170:171], v[108:109], v[44:45], v[170:171]
	v_pk_fma_f32 v[170:171], v[110:111], v[42:43], v[170:171]
	ds_read_b128 v[104:107], v67 offset:6144
	s_waitcnt lgkmcnt(6)
	v_pk_fma_f32 v[172:173], v[112:113], v[44:45], v[172:173]
	v_pk_fma_f32 v[172:173], v[114:115], v[42:43], v[172:173]
	ds_read_b128 v[108:111], v67 offset:10240
	s_waitcnt lgkmcnt(6)
	v_pk_fma_f32 v[174:175], v[116:117], v[44:45], v[174:175]
	v_pk_fma_f32 v[174:175], v[118:119], v[42:43], v[174:175]
	ds_read_b128 v[112:115], v67 offset:14336
	s_waitcnt lgkmcnt(6)
	v_pk_fma_f32 v[176:177], v[120:121], v[44:45], v[176:177]
	v_pk_fma_f32 v[176:177], v[122:123], v[42:43], v[176:177]
	ds_read_b128 v[116:119], v67 offset:18432
	s_waitcnt lgkmcnt(6)
	v_pk_fma_f32 v[178:179], v[124:125], v[44:45], v[178:179]
	v_pk_fma_f32 v[178:179], v[126:127], v[42:43], v[178:179]
	ds_read_b128 v[120:123], v67 offset:22528
	s_waitcnt lgkmcnt(6)
	v_pk_fma_f32 v[180:181], v[128:129], v[44:45], v[180:181]
	v_pk_fma_f32 v[180:181], v[130:131], v[42:43], v[180:181]
	v_pk_mul_f32 v[42:43], v[38:39], v[58:59] op_sel_hi:[1,0]
	v_pk_mul_f32 v[38:39], v[40:41], v[58:59] op_sel_hi:[1,0]
	v_pk_mul_f32 v[40:41], v[6:7], v[42:43]
	v_pk_mul_f32 v[38:39], v[8:9], v[38:39]
	v_cvt_pk_bf16_f32 v42, v40, v41
	v_cvt_pk_bf16_f32 v43, v38, v39
	global_store_dwordx2 v[46:47], v[42:43], off offset:1024
	ds_read_b128 v[124:127], v67 offset:26624
	ds_read_b128 v[128:131], v67 offset:30720
	s_waitcnt lgkmcnt(7)
	v_pk_fma_f32 v[148:149], v[100:101], v[40:41], v[148:149]
	v_pk_fma_f32 v[148:149], v[102:103], v[38:39], v[148:149]
	s_waitcnt lgkmcnt(6)
	v_pk_fma_f32 v[150:151], v[104:105], v[40:41], v[150:151]
	v_pk_fma_f32 v[150:151], v[106:107], v[38:39], v[150:151]
	ds_read_b128 v[100:103], v67 offset:34816
	s_waitcnt lgkmcnt(6)
	v_pk_fma_f32 v[152:153], v[108:109], v[40:41], v[152:153]
	v_pk_fma_f32 v[152:153], v[110:111], v[38:39], v[152:153]
	ds_read_b128 v[104:107], v67 offset:38912
	s_waitcnt lgkmcnt(6)
	v_pk_fma_f32 v[154:155], v[112:113], v[40:41], v[154:155]
	v_pk_fma_f32 v[154:155], v[114:115], v[38:39], v[154:155]
	ds_read_b128 v[108:111], v67 offset:43008
	s_waitcnt lgkmcnt(6)
	v_pk_fma_f32 v[156:157], v[116:117], v[40:41], v[156:157]
	v_pk_fma_f32 v[156:157], v[118:119], v[38:39], v[156:157]
	ds_read_b128 v[112:115], v67 offset:47104
	s_waitcnt lgkmcnt(6)
	v_pk_fma_f32 v[158:159], v[120:121], v[40:41], v[158:159]
	v_pk_fma_f32 v[158:159], v[122:123], v[38:39], v[158:159]
	ds_read_b128 v[116:119], v67 offset:51200
	s_waitcnt lgkmcnt(6)
	v_pk_fma_f32 v[160:161], v[124:125], v[40:41], v[160:161]
	v_pk_fma_f32 v[160:161], v[126:127], v[38:39], v[160:161]
	ds_read_b128 v[120:123], v67 offset:55296
	s_waitcnt lgkmcnt(6)
	v_pk_fma_f32 v[162:163], v[128:129], v[40:41], v[162:163]
	v_pk_fma_f32 v[162:163], v[130:131], v[38:39], v[162:163]
	ds_read_b128 v[124:127], v67 offset:59392
	s_waitcnt lgkmcnt(6)
	v_pk_fma_f32 v[164:165], v[100:101], v[40:41], v[164:165]
	v_pk_fma_f32 v[164:165], v[102:103], v[38:39], v[164:165]
	ds_read_b128 v[128:131], v67 offset:63488
	s_waitcnt lgkmcnt(6)
	v_pk_fma_f32 v[168:169], v[104:105], v[40:41], v[168:169]
	v_pk_fma_f32 v[168:169], v[106:107], v[38:39], v[168:169]
	ds_read_b128 v[100:103], v67 offset:3072
	s_waitcnt lgkmcnt(6)
	v_pk_fma_f32 v[170:171], v[108:109], v[40:41], v[170:171]
	v_pk_fma_f32 v[170:171], v[110:111], v[38:39], v[170:171]
	ds_read_b128 v[104:107], v67 offset:7168
	s_waitcnt lgkmcnt(6)
	v_pk_fma_f32 v[172:173], v[112:113], v[40:41], v[172:173]
	v_pk_fma_f32 v[172:173], v[114:115], v[38:39], v[172:173]
	ds_read_b128 v[108:111], v67 offset:11264
	s_waitcnt lgkmcnt(6)
	v_pk_fma_f32 v[174:175], v[116:117], v[40:41], v[174:175]
	v_pk_fma_f32 v[174:175], v[118:119], v[38:39], v[174:175]
	ds_read_b128 v[112:115], v67 offset:15360
	s_waitcnt lgkmcnt(6)
; #define LAS __attribute__((address_space(3)))
; __device__ void phase_norm_alow(const Params& P, int l, int half, LAS unsigned char* lds) {
;     ...
;             for (int c = 0; c < 16; ++c) { const f32x4 wv = *(const LAS f32x4*)(WaT + c * 1024 + i * 256 + lane * 4); a[c] += h[0] * wv[0] + h[1] * wv[1] + h[2] * wv[2] + h[3] * wv[3]; } }
;         float b8[8], b4[4], b2[2], b1;
;         { const bool up = (lane & 32) != 0;
; #pragma unroll
;           for (int c = 0; c < 8; ++c) { const float keep = up ? a[c + 8] : a[c], send = up ? a[c] : a[c + 8]; b8[c] = keep + __shfl_xor(send, 32); } }
;         { const bool up = (lane & 16) != 0;
; #pragma unroll
;           for (int c = 0; c < 4; ++c) { const float keep = up ? b8[c + 4] : b8[c], send = up ? b8[c] : b8[c + 4]; b4[c] = keep + __shfl_xor(send, 16); } }
;         { const bool up = (lane & 8) != 0;
; #pragma unroll
;           for (int c = 0; c < 2; ++c) { const float keep = up ? b4[c + 2] : b4[c], send = up ? b4[c] : b4[c + 2]; b2[c] = keep + __shfl_xor(send, 8); } }
;         { const bool up = (lane & 4) != 0; const float keep = up ? b2[1] : b2[0], send = up ? b2[0] : b2[1]; b1 = keep + __shfl_xor(send, 4); }
;         b1 += __shfl_xor(b1, 2); b1 += __shfl_xor(b1, 1);
;         if ((lane & 3) == 0) { const int co = ((lane >> 5) & 1) * 8 + ((lane >> 4) & 1) * 4 + ((lane >> 3) & 1) * 2 + ((lane >> 2) & 1); AL[(size_t)row * 16 + co] = b1; }
	v_pk_fma_f32 v[176:177], v[120:121], v[40:41], v[176:177]
	v_pk_fma_f32 v[176:177], v[122:123], v[38:39], v[176:177]
	ds_read_b128 v[116:119], v67 offset:19456
	s_waitcnt lgkmcnt(6)
	v_pk_fma_f32 v[178:179], v[124:125], v[40:41], v[178:179]
	v_pk_fma_f32 v[178:179], v[126:127], v[38:39], v[178:179]
	ds_read_b128 v[120:123], v67 offset:23552
	s_waitcnt lgkmcnt(6)
	v_pk_fma_f32 v[180:181], v[128:129], v[40:41], v[180:181]
	v_pk_fma_f32 v[180:181], v[130:131], v[38:39], v[180:181]
	v_pk_mul_f32 v[40:41], v[34:35], v[58:59] op_sel_hi:[1,0]
	v_pk_mul_f32 v[34:35], v[36:37], v[58:59] op_sel_hi:[1,0]
	v_pk_mul_f32 v[36:37], v[2:3], v[40:41]
	v_pk_mul_f32 v[34:35], v[4:5], v[34:35]
	v_cvt_pk_bf16_f32 v40, v36, v37
	s_nop 0
	v_cvt_pk_bf16_f32 v41, v34, v35
	ds_read_b128 v[124:127], v67 offset:27648
	global_store_dwordx2 v[46:47], v[40:41], off offset:1536
	s_waitcnt lgkmcnt(6)
	v_pk_fma_f32 v[148:149], v[100:101], v[36:37], v[148:149]
	v_pk_fma_f32 v[148:149], v[102:103], v[34:35], v[148:149]
	ds_read_b128 v[128:131], v67 offset:31744
	v_add_f32_e32 v39, v148, v149
	s_waitcnt lgkmcnt(6)
	v_pk_fma_f32 v[150:151], v[104:105], v[36:37], v[150:151]
	v_pk_fma_f32 v[150:151], v[106:107], v[34:35], v[150:151]
	ds_read_b128 v[100:103], v67 offset:35840
	v_add_f32_e32 v40, v150, v151
	s_waitcnt lgkmcnt(6)
	v_pk_fma_f32 v[152:153], v[108:109], v[36:37], v[152:153]
	v_pk_fma_f32 v[152:153], v[110:111], v[34:35], v[152:153]
	ds_read_b128 v[104:107], v67 offset:39936
	v_add_f32_e32 v41, v152, v153
	s_waitcnt lgkmcnt(6)
	v_pk_fma_f32 v[154:155], v[112:113], v[36:37], v[154:155]
	v_pk_fma_f32 v[154:155], v[114:115], v[34:35], v[154:155]
	v_add_f32_e32 v42, v154, v155
	ds_read_b128 v[108:111], v67 offset:44032
	s_waitcnt lgkmcnt(6)
	v_pk_fma_f32 v[156:157], v[116:117], v[36:37], v[156:157]
	v_pk_fma_f32 v[156:157], v[118:119], v[34:35], v[156:157]
	ds_read_b128 v[112:115], v67 offset:48128
	v_add_f32_e32 v43, v156, v157
	s_waitcnt lgkmcnt(6)
	v_pk_fma_f32 v[158:159], v[120:121], v[36:37], v[158:159]
	v_pk_fma_f32 v[158:159], v[122:123], v[34:35], v[158:159]
	v_add_f32_e32 v48, v158, v159
	ds_read_b128 v[116:119], v67 offset:52224
	s_waitcnt lgkmcnt(6)
	v_pk_fma_f32 v[160:161], v[124:125], v[36:37], v[160:161]
	v_pk_fma_f32 v[160:161], v[126:127], v[34:35], v[160:161]
	v_add_f32_e32 v49, v160, v161
	ds_read_b128 v[120:123], v67 offset:56320
	s_waitcnt lgkmcnt(6)
	v_pk_fma_f32 v[162:163], v[128:129], v[36:37], v[162:163]
	v_pk_fma_f32 v[162:163], v[130:131], v[34:35], v[162:163]
	v_add_f32_e32 v51, v162, v163
	ds_read_b128 v[124:127], v67 offset:60416
	s_waitcnt lgkmcnt(6)
	v_pk_fma_f32 v[164:165], v[100:101], v[36:37], v[164:165]
	v_pk_fma_f32 v[164:165], v[102:103], v[34:35], v[164:165]
	v_add_f32_e32 v58, v164, v165
	ds_read_b128 v[128:131], v67 offset:64512
	s_waitcnt lgkmcnt(6)
	v_pk_fma_f32 v[168:169], v[104:105], v[36:37], v[168:169]
	v_pk_fma_f32 v[168:169], v[106:107], v[34:35], v[168:169]
	v_add_f32_e32 v60, v168, v169
	s_waitcnt lgkmcnt(5)
	v_pk_fma_f32 v[170:171], v[108:109], v[36:37], v[170:171]
	v_pk_fma_f32 v[170:171], v[110:111], v[34:35], v[170:171]
	v_add_f32_e32 v61, v170, v171
	s_waitcnt lgkmcnt(4)
	v_pk_fma_f32 v[172:173], v[112:113], v[36:37], v[172:173]
	v_pk_fma_f32 v[172:173], v[114:115], v[34:35], v[172:173]
	v_add_f32_e32 v68, v172, v173
	s_waitcnt lgkmcnt(3)
	v_pk_fma_f32 v[174:175], v[116:117], v[36:37], v[174:175]
	v_pk_fma_f32 v[174:175], v[118:119], v[34:35], v[174:175]
	v_add_f32_e32 v69, v174, v175
	s_waitcnt lgkmcnt(2)
	v_pk_fma_f32 v[176:177], v[120:121], v[36:37], v[176:177]
	v_pk_fma_f32 v[176:177], v[122:123], v[34:35], v[176:177]
	v_add_f32_e32 v70, v176, v177
	s_waitcnt lgkmcnt(1)
	v_pk_fma_f32 v[178:179], v[124:125], v[36:37], v[178:179]
	v_pk_fma_f32 v[178:179], v[126:127], v[34:35], v[178:179]
	v_add_f32_e32 v71, v178, v179
	s_waitcnt lgkmcnt(0)
	v_pk_fma_f32 v[180:181], v[128:129], v[36:37], v[180:181]
	v_pk_fma_f32 v[180:181], v[130:131], v[34:35], v[180:181]
	v_add_f32_e32 v34, v180, v181
	s_waitcnt lgkmcnt(2)
	s_waitcnt lgkmcnt(2)
	s_waitcnt lgkmcnt(2)
	s_waitcnt lgkmcnt(3)
	s_waitcnt lgkmcnt(2)
	s_waitcnt lgkmcnt(1)
	s_waitcnt lgkmcnt(0)
	s_waitcnt lgkmcnt(0)
	s_waitcnt lgkmcnt(1)
	s_waitcnt lgkmcnt(1)
	s_waitcnt lgkmcnt(0)
	s_waitcnt lgkmcnt(1)
	s_waitcnt lgkmcnt(1)
	s_waitcnt lgkmcnt(0)
	s_waitcnt lgkmcnt(0)
	s_nop 1
	v_permlane32_swap_b32_e32 v39, v58
	s_nop 1
	v_add_f32_e32 v39, v39, v58
	s_nop 1
	v_permlane32_swap_b32_e32 v40, v60
	s_nop 1
	v_add_f32_e32 v40, v40, v60
	s_nop 1
	v_permlane32_swap_b32_e32 v41, v61
	s_nop 1
	v_add_f32_e32 v41, v41, v61
	s_nop 1
	v_permlane32_swap_b32_e32 v42, v68
	s_nop 1
	v_add_f32_e32 v42, v42, v68
	s_nop 1
	v_permlane32_swap_b32_e32 v43, v69
	s_nop 1
	v_add_f32_e32 v43, v43, v69
	s_nop 1
	v_permlane32_swap_b32_e32 v48, v70
	s_nop 1
	v_add_f32_e32 v48, v48, v70
	s_nop 1
	v_permlane32_swap_b32_e32 v49, v71
	s_nop 1
	v_add_f32_e32 v49, v49, v71
	s_nop 1
	v_permlane32_swap_b32_e32 v51, v34
	s_nop 1
	v_add_f32_e32 v51, v51, v34
	s_nop 1
	v_permlane16_swap_b32_e32 v40, v48
	s_nop 1
	v_add_f32_e32 v40, v40, v48
	s_nop 1
	v_permlane16_swap_b32_e32 v39, v43
	s_nop 1
	v_add_f32_e32 v39, v39, v43
	s_nop 1
	v_permlane16_swap_b32_e32 v41, v49
	s_nop 1
	v_add_f32_e32 v41, v41, v49
	s_nop 1
	v_permlane16_swap_b32_e32 v42, v51
	s_nop 1
	v_add_f32_e32 v42, v42, v51
	s_nop 1
	v_add_f32_dpp v39, v39, v39 row_ror:8 row_mask:0xf bank_mask:0x3
	s_nop 1
	v_add_f32_dpp v39, v41, v41 row_ror:8 row_mask:0xf bank_mask:0xc
	s_nop 1
	v_add_f32_dpp v40, v40, v40 row_ror:8 row_mask:0xf bank_mask:0x3
	s_nop 1
	v_add_f32_dpp v40, v42, v42 row_ror:8 row_mask:0xf bank_mask:0xc
	s_nop 1
	v_add_f32_dpp v39, v39, v39 row_shl:4 row_mask:0xf bank_mask:0x5
	s_nop 1
	v_add_f32_dpp v39, v40, v40 row_shr:4 row_mask:0xf bank_mask:0xa
	v_mov_b32_e32 v34, v39
	s_nop 0
	s_nop 1
	v_mov_b32_dpp v35, v34 quad_perm:[2,3,0,1] row_mask:0xf bank_mask:0xf
	s_waitcnt lgkmcnt(0)
	v_add_f32_e32 v34, v34, v35
	s_nop 1
	v_mov_b32_dpp v35, v34 quad_perm:[1,0,3,2] row_mask:0xf bank_mask:0xf
	s_and_saveexec_b64 s[0:1], s[42:43]
	s_cbranch_execz .LBB0_239
	v_lshl_add_u64 v[36:37], s[74:75], 0, v[52:53]
	s_waitcnt lgkmcnt(0)
	v_add_f32_e32 v34, v34, v35
	global_store_dword v[36:37], v34, off
	s_branch .LBB0_239

; #define LAS __attribute__((address_space(3)))
; __device__ __forceinline__ unsigned cvt_pk_bf16(float lo, float hi) { unsigned r; asm volatile("v_cvt_pk_bf16_f32 %0, %1, %2" : "=v"(r) : "v"(lo), "v"(hi)); return r; }
; __device__ void phase_norm_alow(const Params& P, int l, int half, LAS unsigned char* lds) {
;     ...
;         f32x4 v[4]; float ss = 0.f;
; #pragma unroll
;         for (int i = 0; i < 4; ++i) { v[i] = nv[i]; ss += v[i][0] * v[i][0] + v[i][1] * v[i][1] + v[i][2] * v[i][2] + v[i][3] * v[i][3]; }
;         if (row + rstride < TH) {
; #pragma unroll
;             for (int i = 0; i < 4; ++i) nv[i] = *(const f32x4*)(xs + (size_t)(row + rstride) * DM + i * 256 + lane * 4);
;         }
;         ss = wave_sum(ss);
;         const float r = rsqrtf(ss * (1.0f / DM) + EPS);
;         float a[16];
; #pragma unroll
;         for (int c = 0; c < 16; ++c) a[c] = 0.f;
; #pragma unroll
;         for (int i = 0; i < 4; ++i) { f32x4 h = v[i] * r * gv[i];
;             u32x2 w; w.x = cvt_pk_bf16(h[0], h[1]); w.y = cvt_pk_bf16(h[2], h[3]);
;             *(u32x2*)(H + (size_t)row * DM + i * 256 + lane * 4) = w;
; #pragma unroll
;             for (int c = 0; c < 16; ++c) { const f32x4 wv = *(const LAS f32x4*)(WaT + c * 1024 + i * 256 + lane * 4); a[c] += h[0] * wv[0] + h[1] * wv[1] + h[2] * wv[2] + h[3] * wv[3]; } }
.LBB0_680:
	s_or_b64 exec, exec, s[30:31]
	v_mul_f32_e32 v51, v47, v47
	v_mul_f32_e32 v58, v43, v43
	v_fmac_f32_e32 v51, v46, v46
	v_fmac_f32_e32 v58, v42, v42
	v_fmac_f32_e32 v51, v48, v48
	v_fmac_f32_e32 v58, v44, v44
	v_fmac_f32_e32 v51, v49, v49
	v_fmac_f32_e32 v58, v45, v45
	v_add_f32_e32 v51, v51, v58
	v_mul_f32_e32 v58, v39, v39
	v_fmac_f32_e32 v58, v38, v38
	v_fmac_f32_e32 v58, v40, v40
	v_fmac_f32_e32 v58, v41, v41
	v_add_f32_e32 v51, v51, v58
	v_mul_f32_e32 v58, v35, v35
	v_fmac_f32_e32 v58, v34, v34
	v_fmac_f32_e32 v58, v36, v36
	v_fmac_f32_e32 v58, v37, v37
	v_add_f32_e32 v51, v51, v58
	v_mov_b32_e32 v58, v51
	s_nop 1
	v_permlane32_swap_b32_e32 v58, v51
	s_nop 1
	v_lshl_add_u64 v[68:69], s[74:75], 0, v[56:57]
	s_waitcnt lgkmcnt(0)
	v_add_f32_e32 v51, v51, v58
	v_mov_b32_e32 v58, v51
	s_nop 1
	v_permlane16_swap_b32_e32 v58, v51
	s_nop 1
	s_waitcnt lgkmcnt(0)
	v_add_f32_e32 v51, v51, v58
	s_nop 1
	v_mov_b32_dpp v58, v51 row_ror:8 row_mask:0xf bank_mask:0xf
	s_waitcnt lgkmcnt(0)
	v_add_f32_e32 v51, v51, v58
	s_nop 1
	v_mov_b32_dpp v58, v51 row_shl:4 row_mask:0xf bank_mask:0x5
	s_nop 1
	v_mov_b32_dpp v58, v51 row_shr:4 row_mask:0xf bank_mask:0xa
	s_waitcnt lgkmcnt(0)
	v_add_f32_e32 v51, v51, v58
	s_nop 1
	v_mov_b32_dpp v58, v51 quad_perm:[2,3,0,1] row_mask:0xf bank_mask:0xf
	s_waitcnt lgkmcnt(0)
	v_add_f32_e32 v51, v51, v58
	s_nop 1
	v_mov_b32_dpp v58, v51 quad_perm:[1,0,3,2] row_mask:0xf bank_mask:0xf
	s_waitcnt lgkmcnt(0)
	v_add_f32_e32 v51, v51, v58
	v_fmamk_f32 v51, v51, 0x3a800000, v1
	v_cmp_gt_f32_e64 s[0:1], s33, v51
	v_mul_f32_e32 v58, 0x4b800000, v51
	s_nop 0
	v_cndmask_b32_e64 v51, v51, v58, s[0:1]
	v_rsq_f32_e32 v51, v51
	s_nop 0
	v_mul_f32_e32 v58, 0x45800000, v51
	v_cndmask_b32_e64 v58, v51, v58, s[0:1]
	v_pk_mul_f32 v[46:47], v[46:47], v[58:59] op_sel_hi:[1,0]
	s_mov_b32 s0, 0x3a88000
	v_pk_mul_f32 v[48:49], v[48:49], v[58:59] op_sel_hi:[1,0]
	v_pk_mul_f32 v[60:61], v[14:15], v[46:47]
	v_add_co_u32_e64 v46, s[0:1], s0, v68
	v_pk_mul_f32 v[48:49], v[16:17], v[48:49]
	v_cvt_pk_bf16_f32 v70, v60, v61
	s_nop 0
	v_addc_co_u32_e64 v47, s[0:1], 0, v69, s[0:1]
	v_cvt_pk_bf16_f32 v71, v48, v49
	global_store_dwordx2 v[46:47], v[70:71], off
	ds_read_b128 v[100:103], v67
	ds_read_b128 v[104:107], v67 offset:4096
	ds_read_b128 v[108:111], v67 offset:8192
	ds_read_b128 v[112:115], v67 offset:12288
	ds_read_b128 v[116:119], v67 offset:16384
	ds_read_b128 v[120:123], v67 offset:20480
	ds_read_b128 v[124:127], v67 offset:24576
	s_waitcnt lgkmcnt(6)
	v_pk_mul_f32 v[148:149], v[100:101], v[60:61]
	v_pk_fma_f32 v[148:149], v[102:103], v[48:49], v[148:149]
	ds_read_b128 v[128:131], v67 offset:28672
	s_waitcnt lgkmcnt(6)
	v_pk_mul_f32 v[150:151], v[104:105], v[60:61]
	v_pk_fma_f32 v[150:151], v[106:107], v[48:49], v[150:151]
	ds_read_b128 v[100:103], v67 offset:32768
	s_waitcnt lgkmcnt(6)
	v_pk_mul_f32 v[152:153], v[108:109], v[60:61]
	v_pk_fma_f32 v[152:153], v[110:111], v[48:49], v[152:153]
	ds_read_b128 v[104:107], v67 offset:36864
	s_waitcnt lgkmcnt(6)
	v_pk_mul_f32 v[154:155], v[112:113], v[60:61]
	v_pk_fma_f32 v[154:155], v[114:115], v[48:49], v[154:155]
	ds_read_b128 v[108:111], v67 offset:40960
	s_waitcnt lgkmcnt(6)
	v_pk_mul_f32 v[156:157], v[116:117], v[60:61]
	v_pk_fma_f32 v[156:157], v[118:119], v[48:49], v[156:157]
	ds_read_b128 v[112:115], v67 offset:45056
	s_waitcnt lgkmcnt(6)
	v_pk_mul_f32 v[158:159], v[120:121], v[60:61]
	v_pk_fma_f32 v[158:159], v[122:123], v[48:49], v[158:159]
	ds_read_b128 v[116:119], v67 offset:49152
	s_waitcnt lgkmcnt(6)
	v_pk_mul_f32 v[160:161], v[124:125], v[60:61]
	v_pk_fma_f32 v[160:161], v[126:127], v[48:49], v[160:161]
	ds_read_b128 v[120:123], v67 offset:53248
	s_waitcnt lgkmcnt(6)
	v_pk_mul_f32 v[162:163], v[128:129], v[60:61]
	v_pk_fma_f32 v[162:163], v[130:131], v[48:49], v[162:163]
	ds_read_b128 v[124:127], v67 offset:57344
	s_waitcnt lgkmcnt(6)
	v_pk_mul_f32 v[164:165], v[100:101], v[60:61]
	v_pk_fma_f32 v[164:165], v[102:103], v[48:49], v[164:165]
	ds_read_b128 v[128:131], v67 offset:61440
	s_waitcnt lgkmcnt(6)
	v_pk_mul_f32 v[168:169], v[104:105], v[60:61]
	v_pk_fma_f32 v[168:169], v[106:107], v[48:49], v[168:169]
	ds_read_b128 v[100:103], v67 offset:1024
	s_waitcnt lgkmcnt(6)
	v_pk_mul_f32 v[170:171], v[108:109], v[60:61]
	v_pk_fma_f32 v[170:171], v[110:111], v[48:49], v[170:171]
	ds_read_b128 v[104:107], v67 offset:5120
	s_waitcnt lgkmcnt(6)
	v_pk_mul_f32 v[172:173], v[112:113], v[60:61]
	v_pk_fma_f32 v[172:173], v[114:115], v[48:49], v[172:173]
	ds_read_b128 v[108:111], v67 offset:9216
	s_waitcnt lgkmcnt(6)
	v_pk_mul_f32 v[174:175], v[116:117], v[60:61]
	v_pk_fma_f32 v[174:175], v[118:119], v[48:49], v[174:175]
	ds_read_b128 v[112:115], v67 offset:13312
	s_waitcnt lgkmcnt(6)
	v_pk_mul_f32 v[176:177], v[120:121], v[60:61]
	v_pk_fma_f32 v[176:177], v[122:123], v[48:49], v[176:177]
	ds_read_b128 v[116:119], v67 offset:17408
	s_waitcnt lgkmcnt(6)
	v_pk_mul_f32 v[178:179], v[124:125], v[60:61]
	v_pk_fma_f32 v[178:179], v[126:127], v[48:49], v[178:179]
	ds_read_b128 v[120:123], v67 offset:21504
	s_waitcnt lgkmcnt(6)
	v_pk_mul_f32 v[180:181], v[128:129], v[60:61]
	v_pk_fma_f32 v[180:181], v[130:131], v[48:49], v[180:181]
	v_pk_mul_f32 v[60:61], v[42:43], v[58:59] op_sel_hi:[1,0]
	v_pk_mul_f32 v[42:43], v[44:45], v[58:59] op_sel_hi:[1,0]
	v_pk_mul_f32 v[44:45], v[10:11], v[60:61]
	v_pk_mul_f32 v[42:43], v[12:13], v[42:43]
	v_cvt_pk_bf16_f32 v60, v44, v45
	s_nop 0
	v_cvt_pk_bf16_f32 v61, v42, v43
	ds_read_b128 v[124:127], v67 offset:25600
	global_store_dwordx2 v[46:47], v[60:61], off offset:512
	s_waitcnt lgkmcnt(6)
; #define LAS __attribute__((address_space(3)))
; __device__ __forceinline__ unsigned cvt_pk_bf16(float lo, float hi) { unsigned r; asm volatile("v_cvt_pk_bf16_f32 %0, %1, %2" : "=v"(r) : "v"(lo), "v"(hi)); return r; }
; __device__ void phase_norm_alow(const Params& P, int l, int half, LAS unsigned char* lds) {
;     ...
;         for (int i = 0; i < 4; ++i) { f32x4 h = v[i] * r * gv[i];
;             u32x2 w; w.x = cvt_pk_bf16(h[0], h[1]); w.y = cvt_pk_bf16(h[2], h[3]);
;             *(u32x2*)(H + (size_t)row * DM + i * 256 + lane * 4) = w;
; #pragma unroll
;             for (int c = 0; c < 16; ++c) { const f32x4 wv = *(const LAS f32x4*)(WaT + c * 1024 + i * 256 + lane * 4); a[c] += h[0] * wv[0] + h[1] * wv[1] + h[2] * wv[2] + h[3] * wv[3]; } }
	v_pk_fma_f32 v[148:149], v[100:101], v[44:45], v[148:149]
	v_pk_fma_f32 v[148:149], v[102:103], v[42:43], v[148:149]
	ds_read_b128 v[128:131], v67 offset:29696
	s_waitcnt lgkmcnt(6)
	v_pk_fma_f32 v[150:151], v[104:105], v[44:45], v[150:151]
	v_pk_fma_f32 v[150:151], v[106:107], v[42:43], v[150:151]
	ds_read_b128 v[100:103], v67 offset:33792
	s_waitcnt lgkmcnt(6)
	v_pk_fma_f32 v[152:153], v[108:109], v[44:45], v[152:153]
	v_pk_fma_f32 v[152:153], v[110:111], v[42:43], v[152:153]
	ds_read_b128 v[104:107], v67 offset:37888
	s_waitcnt lgkmcnt(6)
	v_pk_fma_f32 v[154:155], v[112:113], v[44:45], v[154:155]
	v_pk_fma_f32 v[154:155], v[114:115], v[42:43], v[154:155]
	ds_read_b128 v[108:111], v67 offset:41984
	s_waitcnt lgkmcnt(6)
	v_pk_fma_f32 v[156:157], v[116:117], v[44:45], v[156:157]
	v_pk_fma_f32 v[156:157], v[118:119], v[42:43], v[156:157]
	ds_read_b128 v[112:115], v67 offset:46080
	s_waitcnt lgkmcnt(6)
	v_pk_fma_f32 v[158:159], v[120:121], v[44:45], v[158:159]
	v_pk_fma_f32 v[158:159], v[122:123], v[42:43], v[158:159]
	ds_read_b128 v[116:119], v67 offset:50176
	s_waitcnt lgkmcnt(6)
	v_pk_fma_f32 v[160:161], v[124:125], v[44:45], v[160:161]
	v_pk_fma_f32 v[160:161], v[126:127], v[42:43], v[160:161]
	ds_read_b128 v[120:123], v67 offset:54272
	s_waitcnt lgkmcnt(6)
	v_pk_fma_f32 v[162:163], v[128:129], v[44:45], v[162:163]
	v_pk_fma_f32 v[162:163], v[130:131], v[42:43], v[162:163]
	ds_read_b128 v[124:127], v67 offset:58368
	s_waitcnt lgkmcnt(6)
	v_pk_fma_f32 v[164:165], v[100:101], v[44:45], v[164:165]
	v_pk_fma_f32 v[164:165], v[102:103], v[42:43], v[164:165]
	ds_read_b128 v[128:131], v67 offset:62464
	s_waitcnt lgkmcnt(6)
	v_pk_fma_f32 v[168:169], v[104:105], v[44:45], v[168:169]
	v_pk_fma_f32 v[168:169], v[106:107], v[42:43], v[168:169]
	ds_read_b128 v[100:103], v67 offset:2048
	s_waitcnt lgkmcnt(6)
	v_pk_fma_f32 v[170:171], v[108:109], v[44:45], v[170:171]
	v_pk_fma_f32 v[170:171], v[110:111], v[42:43], v[170:171]
	ds_read_b128 v[104:107], v67 offset:6144
	s_waitcnt lgkmcnt(6)
	v_pk_fma_f32 v[172:173], v[112:113], v[44:45], v[172:173]
	v_pk_fma_f32 v[172:173], v[114:115], v[42:43], v[172:173]
	ds_read_b128 v[108:111], v67 offset:10240
	s_waitcnt lgkmcnt(6)
	v_pk_fma_f32 v[174:175], v[116:117], v[44:45], v[174:175]
	v_pk_fma_f32 v[174:175], v[118:119], v[42:43], v[174:175]
	ds_read_b128 v[112:115], v67 offset:14336
	s_waitcnt lgkmcnt(6)
	v_pk_fma_f32 v[176:177], v[120:121], v[44:45], v[176:177]
	v_pk_fma_f32 v[176:177], v[122:123], v[42:43], v[176:177]
	ds_read_b128 v[116:119], v67 offset:18432
	s_waitcnt lgkmcnt(6)
	v_pk_fma_f32 v[178:179], v[124:125], v[44:45], v[178:179]
	v_pk_fma_f32 v[178:179], v[126:127], v[42:43], v[178:179]
	ds_read_b128 v[120:123], v67 offset:22528
	s_waitcnt lgkmcnt(6)
	v_pk_fma_f32 v[180:181], v[128:129], v[44:45], v[180:181]
	v_pk_fma_f32 v[180:181], v[130:131], v[42:43], v[180:181]
	v_pk_mul_f32 v[42:43], v[38:39], v[58:59] op_sel_hi:[1,0]
	v_pk_mul_f32 v[38:39], v[40:41], v[58:59] op_sel_hi:[1,0]
	v_pk_mul_f32 v[40:41], v[6:7], v[42:43]
	v_pk_mul_f32 v[38:39], v[8:9], v[38:39]
	v_cvt_pk_bf16_f32 v42, v40, v41
	v_cvt_pk_bf16_f32 v43, v38, v39
	global_store_dwordx2 v[46:47], v[42:43], off offset:1024
	ds_read_b128 v[124:127], v67 offset:26624
	ds_read_b128 v[128:131], v67 offset:30720
	s_waitcnt lgkmcnt(7)
	v_pk_fma_f32 v[148:149], v[100:101], v[40:41], v[148:149]
	v_pk_fma_f32 v[148:149], v[102:103], v[38:39], v[148:149]
	s_waitcnt lgkmcnt(6)
	v_pk_fma_f32 v[150:151], v[104:105], v[40:41], v[150:151]
	v_pk_fma_f32 v[150:151], v[106:107], v[38:39], v[150:151]
	ds_read_b128 v[100:103], v67 offset:34816
	s_waitcnt lgkmcnt(6)
	v_pk_fma_f32 v[152:153], v[108:109], v[40:41], v[152:153]
	v_pk_fma_f32 v[152:153], v[110:111], v[38:39], v[152:153]
	ds_read_b128 v[104:107], v67 offset:38912
	s_waitcnt lgkmcnt(6)
	v_pk_fma_f32 v[154:155], v[112:113], v[40:41], v[154:155]
	v_pk_fma_f32 v[154:155], v[114:115], v[38:39], v[154:155]
	ds_read_b128 v[108:111], v67 offset:43008
	s_waitcnt lgkmcnt(6)
	v_pk_fma_f32 v[156:157], v[116:117], v[40:41], v[156:157]
	v_pk_fma_f32 v[156:157], v[118:119], v[38:39], v[156:157]
	ds_read_b128 v[112:115], v67 offset:47104
	s_waitcnt lgkmcnt(6)
	v_pk_fma_f32 v[158:159], v[120:121], v[40:41], v[158:159]
	v_pk_fma_f32 v[158:159], v[122:123], v[38:39], v[158:159]
	ds_read_b128 v[116:119], v67 offset:51200
	s_waitcnt lgkmcnt(6)
	v_pk_fma_f32 v[160:161], v[124:125], v[40:41], v[160:161]
	v_pk_fma_f32 v[160:161], v[126:127], v[38:39], v[160:161]
	ds_read_b128 v[120:123], v67 offset:55296
	s_waitcnt lgkmcnt(6)
	v_pk_fma_f32 v[162:163], v[128:129], v[40:41], v[162:163]
	v_pk_fma_f32 v[162:163], v[130:131], v[38:39], v[162:163]
	ds_read_b128 v[124:127], v67 offset:59392
	s_waitcnt lgkmcnt(6)
	v_pk_fma_f32 v[164:165], v[100:101], v[40:41], v[164:165]
	v_pk_fma_f32 v[164:165], v[102:103], v[38:39], v[164:165]
	ds_read_b128 v[128:131], v67 offset:63488
	s_waitcnt lgkmcnt(6)
	v_pk_fma_f32 v[168:169], v[104:105], v[40:41], v[168:169]
	v_pk_fma_f32 v[168:169], v[106:107], v[38:39], v[168:169]
	ds_read_b128 v[100:103], v67 offset:3072
	s_waitcnt lgkmcnt(6)
	v_pk_fma_f32 v[170:171], v[108:109], v[40:41], v[170:171]
	v_pk_fma_f32 v[170:171], v[110:111], v[38:39], v[170:171]
	ds_read_b128 v[104:107], v67 offset:7168
	s_waitcnt lgkmcnt(6)
	v_pk_fma_f32 v[172:173], v[112:113], v[40:41], v[172:173]
	v_pk_fma_f32 v[172:173], v[114:115], v[38:39], v[172:173]
	ds_read_b128 v[108:111], v67 offset:11264
	s_waitcnt lgkmcnt(6)
	v_pk_fma_f32 v[174:175], v[116:117], v[40:41], v[174:175]
	v_pk_fma_f32 v[174:175], v[118:119], v[38:39], v[174:175]
	ds_read_b128 v[112:115], v67 offset:15360
	s_waitcnt lgkmcnt(6)
; #define LAS __attribute__((address_space(3)))
; __device__ void phase_norm_alow(const Params& P, int l, int half, LAS unsigned char* lds) {
;     ...
;             for (int c = 0; c < 16; ++c) { const f32x4 wv = *(const LAS f32x4*)(WaT + c * 1024 + i * 256 + lane * 4); a[c] += h[0] * wv[0] + h[1] * wv[1] + h[2] * wv[2] + h[3] * wv[3]; } }
;         float b8[8], b4[4], b2[2], b1;
;         { const bool up = (lane & 32) != 0;
; #pragma unroll
;           for (int c = 0; c < 8; ++c) { const float keep = up ? a[c + 8] : a[c], send = up ? a[c] : a[c + 8]; b8[c] = keep + __shfl_xor(send, 32); } }
;         { const bool up = (lane & 16) != 0;
; #pragma unroll
;           for (int c = 0; c < 4; ++c) { const float keep = up ? b8[c + 4] : b8[c], send = up ? b8[c] : b8[c + 4]; b4[c] = keep + __shfl_xor(send, 16); } }
;         { const bool up = (lane & 8) != 0;
; #pragma unroll
;           for (int c = 0; c < 2; ++c) { const float keep = up ? b4[c + 2] : b4[c], send = up ? b4[c] : b4[c + 2]; b2[c] = keep + __shfl_xor(send, 8); } }
;         { const bool up = (lane & 4) != 0; const float keep = up ? b2[1] : b2[0], send = up ? b2[0] : b2[1]; b1 = keep + __shfl_xor(send, 4); }
;         b1 += __shfl_xor(b1, 2); b1 += __shfl_xor(b1, 1);
;         if ((lane & 3) == 0) { const int co = ((lane >> 5) & 1) * 8 + ((lane >> 4) & 1) * 4 + ((lane >> 3) & 1) * 2 + ((lane >> 2) & 1); AL[(size_t)row * 16 + co] = b1; }
	v_pk_fma_f32 v[176:177], v[120:121], v[40:41], v[176:177]
	v_pk_fma_f32 v[176:177], v[122:123], v[38:39], v[176:177]
	ds_read_b128 v[116:119], v67 offset:19456
	s_waitcnt lgkmcnt(6)
	v_pk_fma_f32 v[178:179], v[124:125], v[40:41], v[178:179]
	v_pk_fma_f32 v[178:179], v[126:127], v[38:39], v[178:179]
	ds_read_b128 v[120:123], v67 offset:23552
	s_waitcnt lgkmcnt(6)
	v_pk_fma_f32 v[180:181], v[128:129], v[40:41], v[180:181]
	v_pk_fma_f32 v[180:181], v[130:131], v[38:39], v[180:181]
	v_pk_mul_f32 v[40:41], v[34:35], v[58:59] op_sel_hi:[1,0]
	v_pk_mul_f32 v[34:35], v[36:37], v[58:59] op_sel_hi:[1,0]
	v_pk_mul_f32 v[36:37], v[2:3], v[40:41]
	v_pk_mul_f32 v[34:35], v[4:5], v[34:35]
	v_cvt_pk_bf16_f32 v40, v36, v37
	s_nop 0
	v_cvt_pk_bf16_f32 v41, v34, v35
	ds_read_b128 v[124:127], v67 offset:27648
	global_store_dwordx2 v[46:47], v[40:41], off offset:1536
	s_waitcnt lgkmcnt(6)
	v_pk_fma_f32 v[148:149], v[100:101], v[36:37], v[148:149]
	v_pk_fma_f32 v[148:149], v[102:103], v[34:35], v[148:149]
	ds_read_b128 v[128:131], v67 offset:31744
	v_add_f32_e32 v39, v148, v149
	s_waitcnt lgkmcnt(6)
	v_pk_fma_f32 v[150:151], v[104:105], v[36:37], v[150:151]
	v_pk_fma_f32 v[150:151], v[106:107], v[34:35], v[150:151]
	ds_read_b128 v[100:103], v67 offset:35840
	v_add_f32_e32 v40, v150, v151
	s_waitcnt lgkmcnt(6)
	v_pk_fma_f32 v[152:153], v[108:109], v[36:37], v[152:153]
	v_pk_fma_f32 v[152:153], v[110:111], v[34:35], v[152:153]
	ds_read_b128 v[104:107], v67 offset:39936
	v_add_f32_e32 v41, v152, v153
	s_waitcnt lgkmcnt(6)
	v_pk_fma_f32 v[154:155], v[112:113], v[36:37], v[154:155]
	v_pk_fma_f32 v[154:155], v[114:115], v[34:35], v[154:155]
	v_add_f32_e32 v42, v154, v155
	ds_read_b128 v[108:111], v67 offset:44032
	s_waitcnt lgkmcnt(6)
	v_pk_fma_f32 v[156:157], v[116:117], v[36:37], v[156:157]
	v_pk_fma_f32 v[156:157], v[118:119], v[34:35], v[156:157]
	ds_read_b128 v[112:115], v67 offset:48128
	v_add_f32_e32 v43, v156, v157
	s_waitcnt lgkmcnt(6)
	v_pk_fma_f32 v[158:159], v[120:121], v[36:37], v[158:159]
	v_pk_fma_f32 v[158:159], v[122:123], v[34:35], v[158:159]
	v_add_f32_e32 v48, v158, v159
	ds_read_b128 v[116:119], v67 offset:52224
	s_waitcnt lgkmcnt(6)
	v_pk_fma_f32 v[160:161], v[124:125], v[36:37], v[160:161]
	v_pk_fma_f32 v[160:161], v[126:127], v[34:35], v[160:161]
	v_add_f32_e32 v49, v160, v161
	ds_read_b128 v[120:123], v67 offset:56320
	s_waitcnt lgkmcnt(6)
	v_pk_fma_f32 v[162:163], v[128:129], v[36:37], v[162:163]
	v_pk_fma_f32 v[162:163], v[130:131], v[34:35], v[162:163]
	v_add_f32_e32 v51, v162, v163
	ds_read_b128 v[124:127], v67 offset:60416
	s_waitcnt lgkmcnt(6)
	v_pk_fma_f32 v[164:165], v[100:101], v[36:37], v[164:165]
	v_pk_fma_f32 v[164:165], v[102:103], v[34:35], v[164:165]
	v_add_f32_e32 v58, v164, v165
	ds_read_b128 v[128:131], v67 offset:64512
	s_waitcnt lgkmcnt(6)
	v_pk_fma_f32 v[168:169], v[104:105], v[36:37], v[168:169]
	v_pk_fma_f32 v[168:169], v[106:107], v[34:35], v[168:169]
	v_add_f32_e32 v60, v168, v169
	s_waitcnt lgkmcnt(5)
	v_pk_fma_f32 v[170:171], v[108:109], v[36:37], v[170:171]
	v_pk_fma_f32 v[170:171], v[110:111], v[34:35], v[170:171]
	v_add_f32_e32 v61, v170, v171
	s_waitcnt lgkmcnt(4)
	v_pk_fma_f32 v[172:173], v[112:113], v[36:37], v[172:173]
	v_pk_fma_f32 v[172:173], v[114:115], v[34:35], v[172:173]
	v_add_f32_e32 v68, v172, v173
	s_waitcnt lgkmcnt(3)
	v_pk_fma_f32 v[174:175], v[116:117], v[36:37], v[174:175]
	v_pk_fma_f32 v[174:175], v[118:119], v[34:35], v[174:175]
	v_add_f32_e32 v69, v174, v175
	s_waitcnt lgkmcnt(2)
	v_pk_fma_f32 v[176:177], v[120:121], v[36:37], v[176:177]
	v_pk_fma_f32 v[176:177], v[122:123], v[34:35], v[176:177]
	v_add_f32_e32 v70, v176, v177
	s_waitcnt lgkmcnt(1)
	v_pk_fma_f32 v[178:179], v[124:125], v[36:37], v[178:179]
	v_pk_fma_f32 v[178:179], v[126:127], v[34:35], v[178:179]
	v_add_f32_e32 v71, v178, v179
	s_waitcnt lgkmcnt(0)
	v_pk_fma_f32 v[180:181], v[128:129], v[36:37], v[180:181]
	v_pk_fma_f32 v[180:181], v[130:131], v[34:35], v[180:181]
	v_add_f32_e32 v34, v180, v181
	s_waitcnt lgkmcnt(2)
	s_waitcnt lgkmcnt(2)
	s_waitcnt lgkmcnt(2)
	s_waitcnt lgkmcnt(3)
	s_waitcnt lgkmcnt(2)
	s_waitcnt lgkmcnt(1)
	s_waitcnt lgkmcnt(0)
	s_waitcnt lgkmcnt(0)
	s_waitcnt lgkmcnt(1)
	s_waitcnt lgkmcnt(1)
	s_waitcnt lgkmcnt(0)
	s_waitcnt lgkmcnt(1)
	s_waitcnt lgkmcnt(1)
	s_waitcnt lgkmcnt(0)
	s_waitcnt lgkmcnt(0)
	s_nop 1
	v_permlane32_swap_b32_e32 v39, v58
	s_nop 1
	v_add_f32_e32 v39, v39, v58
	s_nop 1
	v_permlane32_swap_b32_e32 v40, v60
	s_nop 1
	v_add_f32_e32 v40, v40, v60
	s_nop 1
	v_permlane32_swap_b32_e32 v41, v61
	s_nop 1
	v_add_f32_e32 v41, v41, v61
	s_nop 1
	v_permlane32_swap_b32_e32 v42, v68
	s_nop 1
	v_add_f32_e32 v42, v42, v68
	s_nop 1
	v_permlane32_swap_b32_e32 v43, v69
	s_nop 1
	v_add_f32_e32 v43, v43, v69
	s_nop 1
	v_permlane32_swap_b32_e32 v48, v70
	s_nop 1
	v_add_f32_e32 v48, v48, v70
	s_nop 1
	v_permlane32_swap_b32_e32 v49, v71
	s_nop 1
	v_add_f32_e32 v49, v49, v71
	s_nop 1
	v_permlane32_swap_b32_e32 v51, v34
	s_nop 1
	v_add_f32_e32 v51, v51, v34
	s_nop 1
	v_permlane16_swap_b32_e32 v40, v48
	s_nop 1
	v_add_f32_e32 v40, v40, v48
	s_nop 1
	v_permlane16_swap_b32_e32 v39, v43
	s_nop 1
	v_add_f32_e32 v39, v39, v43
	s_nop 1
	v_permlane16_swap_b32_e32 v41, v49
	s_nop 1
	v_add_f32_e32 v41, v41, v49
	s_nop 1
	v_permlane16_swap_b32_e32 v42, v51
	s_nop 1
	v_add_f32_e32 v42, v42, v51
	s_nop 1
	v_add_f32_dpp v39, v39, v39 row_ror:8 row_mask:0xf bank_mask:0x3
	s_nop 1
	v_add_f32_dpp v39, v41, v41 row_ror:8 row_mask:0xf bank_mask:0xc
	s_nop 1
	v_add_f32_dpp v40, v40, v40 row_ror:8 row_mask:0xf bank_mask:0x3
	s_nop 1
	v_add_f32_dpp v40, v42, v42 row_ror:8 row_mask:0xf bank_mask:0xc
	s_nop 1
	v_add_f32_dpp v39, v39, v39 row_shl:4 row_mask:0xf bank_mask:0x5
	s_nop 1
	v_add_f32_dpp v39, v40, v40 row_shr:4 row_mask:0xf bank_mask:0xa
	v_mov_b32_e32 v34, v39
	s_nop 0
	s_nop 1
	v_mov_b32_dpp v35, v34 quad_perm:[2,3,0,1] row_mask:0xf bank_mask:0xf
	s_waitcnt lgkmcnt(0)
	v_add_f32_e32 v34, v34, v35
	s_nop 1
	v_mov_b32_dpp v35, v34 quad_perm:[1,0,3,2] row_mask:0xf bank_mask:0xf
	s_and_saveexec_b64 s[0:1], s[42:43]
	s_cbranch_execz .LBB0_677
	v_lshl_add_u64 v[36:37], s[74:75], 0, v[54:55]
	s_waitcnt lgkmcnt(0)
	v_add_f32_e32 v34, v34, v35
	global_store_dword v[36:37], v34, off
	s_branch .LBB0_677

; #define LAS __attribute__((address_space(3)))
; __device__ __forceinline__ unsigned cvt_pk_bf16(float lo, float hi) { unsigned r; asm volatile("v_cvt_pk_bf16_f32 %0, %1, %2" : "=v"(r) : "v"(lo), "v"(hi)); return r; }
; __device__ void phase_norm_alow(const Params& P, int l, int half, LAS unsigned char* lds) {
;     ...
;         f32x4 v[4]; float ss = 0.f;
; #pragma unroll
;         for (int i = 0; i < 4; ++i) { v[i] = nv[i]; ss += v[i][0] * v[i][0] + v[i][1] * v[i][1] + v[i][2] * v[i][2] + v[i][3] * v[i][3]; }
;         if (row + rstride < TH) {
; #pragma unroll
;             for (int i = 0; i < 4; ++i) nv[i] = *(const f32x4*)(xs + (size_t)(row + rstride) * DM + i * 256 + lane * 4);
;         }
;         ss = wave_sum(ss);
;         const float r = rsqrtf(ss * (1.0f / DM) + EPS);
;         float a[16];
; #pragma unroll
;         for (int c = 0; c < 16; ++c) a[c] = 0.f;
; #pragma unroll
;         for (int i = 0; i < 4; ++i) { f32x4 h = v[i] * r * gv[i];
;             u32x2 w; w.x = cvt_pk_bf16(h[0], h[1]); w.y = cvt_pk_bf16(h[2], h[3]);
;             *(u32x2*)(H + (size_t)row * DM + i * 256 + lane * 4) = w;
; #pragma unroll
;             for (int c = 0; c < 16; ++c) { const f32x4 wv = *(const LAS f32x4*)(WaT + c * 1024 + i * 256 + lane * 4); a[c] += h[0] * wv[0] + h[1] * wv[1] + h[2] * wv[2] + h[3] * wv[3]; } }
.LBB0_755:
	s_or_b64 exec, exec, s[46:47]
	v_mul_f32_e32 v51, v47, v47
	v_mul_f32_e32 v58, v43, v43
	v_fmac_f32_e32 v51, v46, v46
	v_fmac_f32_e32 v58, v42, v42
	v_fmac_f32_e32 v51, v48, v48
	v_fmac_f32_e32 v58, v44, v44
	v_fmac_f32_e32 v51, v49, v49
	v_fmac_f32_e32 v58, v45, v45
	v_add_f32_e32 v51, v51, v58
	v_mul_f32_e32 v58, v39, v39
	v_fmac_f32_e32 v58, v38, v38
	v_fmac_f32_e32 v58, v40, v40
	v_fmac_f32_e32 v58, v41, v41
	v_add_f32_e32 v51, v51, v58
	v_mul_f32_e32 v58, v35, v35
	v_fmac_f32_e32 v58, v34, v34
	v_fmac_f32_e32 v58, v36, v36
	v_fmac_f32_e32 v58, v37, v37
	v_add_f32_e32 v51, v51, v58
	v_mov_b32_e32 v58, v51
	s_nop 1
	v_permlane32_swap_b32_e32 v58, v51
	s_nop 1
	s_mov_b32 s2, 0x3a88000
	s_waitcnt lgkmcnt(0)
	v_add_f32_e32 v51, v51, v58
	v_mov_b32_e32 v58, v51
	s_nop 1
	v_permlane16_swap_b32_e32 v58, v51
	s_nop 1
	s_waitcnt lgkmcnt(0)
	v_add_f32_e32 v51, v51, v58
	s_nop 1
	v_mov_b32_dpp v58, v51 row_ror:8 row_mask:0xf bank_mask:0xf
	s_waitcnt lgkmcnt(0)
	v_add_f32_e32 v51, v51, v58
	s_nop 1
	v_mov_b32_dpp v58, v51 row_shl:4 row_mask:0xf bank_mask:0x5
	s_nop 1
	v_mov_b32_dpp v58, v51 row_shr:4 row_mask:0xf bank_mask:0xa
	s_waitcnt lgkmcnt(0)
	v_add_f32_e32 v51, v51, v58
	s_nop 1
	v_mov_b32_dpp v58, v51 quad_perm:[2,3,0,1] row_mask:0xf bank_mask:0xf
	s_waitcnt lgkmcnt(0)
	v_add_f32_e32 v51, v51, v58
	s_nop 1
	v_mov_b32_dpp v60, v51 quad_perm:[1,0,3,2] row_mask:0xf bank_mask:0xf
	v_lshl_add_u64 v[58:59], s[74:75], 0, v[52:53]
	v_add_co_u32_e64 v58, s[46:47], s2, v58
	s_waitcnt lgkmcnt(0)
	v_add_f32_e32 v51, v51, v60
	v_fmamk_f32 v51, v51, 0x3a800000, v1
	v_mul_f32_e32 v60, 0x4b800000, v51
	v_cmp_gt_f32_e64 s[0:1], s33, v51
	v_addc_co_u32_e64 v59, s[46:47], 0, v59, s[46:47]
	s_nop 0
	v_cndmask_b32_e64 v51, v51, v60, s[0:1]
	v_rsq_f32_e32 v51, v51
	s_nop 0
	v_mul_f32_e32 v60, 0x45800000, v51
	v_cndmask_b32_e64 v60, v51, v60, s[0:1]
	v_pk_mul_f32 v[46:47], v[46:47], v[60:61] op_sel_hi:[1,0]
	v_pk_mul_f32 v[48:49], v[48:49], v[60:61] op_sel_hi:[1,0]
	s_waitcnt vmcnt(0)
	v_pk_mul_f32 v[82:83], v[14:15], v[46:47]
	v_pk_mul_f32 v[80:81], v[16:17], v[48:49]
	v_cvt_pk_bf16_f32 v84, v82, v83
	v_pk_mul_f32 v[42:43], v[42:43], v[60:61] op_sel_hi:[1,0]
	v_cvt_pk_bf16_f32 v85, v80, v81
	ds_read_b128 v[100:103], v61
	ds_read_b128 v[104:107], v61 offset:4096
	ds_read_b128 v[108:111], v61 offset:8192
	ds_read_b128 v[112:115], v61 offset:12288
	ds_read_b128 v[116:119], v61 offset:16384
	ds_read_b128 v[120:123], v61 offset:20480
	ds_read_b128 v[124:127], v61 offset:24576
	ds_read_b128 v[128:131], v61 offset:28672
	ds_read_b128 v[132:135], v61 offset:32768
	ds_read_b128 v[136:139], v61 offset:36864
	global_store_dwordx2 v[58:59], v[84:85], off
	s_waitcnt lgkmcnt(9)
	v_pk_mul_f32 v[148:149], v[100:101], v[82:83]
	s_waitcnt lgkmcnt(7)
	v_pk_mul_f32 v[150:151], v[108:109], v[82:83]
	v_pk_mul_f32 v[152:153], v[104:105], v[82:83]
	v_pk_fma_f32 v[148:149], v[102:103], v[80:81], v[148:149]
	v_pk_fma_f32 v[150:151], v[110:111], v[80:81], v[150:151]
	s_waitcnt lgkmcnt(6)
	v_pk_mul_f32 v[154:155], v[112:113], v[82:83]
	ds_read_b128 v[100:103], v61 offset:40960
	v_pk_fma_f32 v[154:155], v[114:115], v[80:81], v[154:155]
	v_pk_fma_f32 v[152:153], v[106:107], v[80:81], v[152:153]
	ds_read_b128 v[104:107], v61 offset:45056
	s_waitcnt lgkmcnt(7)
	v_pk_mul_f32 v[156:157], v[116:117], v[82:83]
	v_pk_fma_f32 v[156:157], v[118:119], v[80:81], v[156:157]
	s_waitcnt lgkmcnt(6)
	v_pk_mul_f32 v[158:159], v[120:121], v[82:83]
	ds_read_b128 v[108:111], v61 offset:49152
	v_pk_fma_f32 v[158:159], v[122:123], v[80:81], v[158:159]
	ds_read_b128 v[112:115], v61 offset:53248
	s_waitcnt lgkmcnt(7)
	v_pk_mul_f32 v[160:161], v[124:125], v[82:83]
	v_pk_fma_f32 v[160:161], v[126:127], v[80:81], v[160:161]
	s_waitcnt lgkmcnt(6)
	v_pk_mul_f32 v[162:163], v[128:129], v[82:83]
	ds_read_b128 v[116:119], v61 offset:57344
	v_pk_fma_f32 v[162:163], v[130:131], v[80:81], v[162:163]
	ds_read_b128 v[120:123], v61 offset:61440
	s_waitcnt lgkmcnt(7)
	v_pk_mul_f32 v[164:165], v[132:133], v[82:83]
	v_pk_fma_f32 v[164:165], v[134:135], v[80:81], v[164:165]
	s_waitcnt lgkmcnt(6)
	v_pk_mul_f32 v[168:169], v[136:137], v[82:83]
	ds_read_b128 v[124:127], v61 offset:1024
	v_pk_fma_f32 v[168:169], v[138:139], v[80:81], v[168:169]
	ds_read_b128 v[128:131], v61 offset:5120
	s_waitcnt lgkmcnt(7)
	v_pk_mul_f32 v[170:171], v[100:101], v[82:83]
	v_pk_fma_f32 v[170:171], v[102:103], v[80:81], v[170:171]
	s_waitcnt lgkmcnt(6)
	v_pk_mul_f32 v[172:173], v[104:105], v[82:83]
	ds_read_b128 v[132:135], v61 offset:9216
	v_pk_fma_f32 v[172:173], v[106:107], v[80:81], v[172:173]
	ds_read_b128 v[136:139], v61 offset:13312
	s_waitcnt lgkmcnt(7)
	v_pk_mul_f32 v[174:175], v[108:109], v[82:83]
	v_pk_fma_f32 v[174:175], v[110:111], v[80:81], v[174:175]
	s_waitcnt lgkmcnt(6)
	v_pk_mul_f32 v[176:177], v[112:113], v[82:83]
	ds_read_b128 v[100:103], v61 offset:17408
	v_pk_fma_f32 v[176:177], v[114:115], v[80:81], v[176:177]
	ds_read_b128 v[104:107], v61 offset:21504
	s_waitcnt lgkmcnt(7)
	v_pk_mul_f32 v[178:179], v[116:117], v[82:83]
	v_pk_fma_f32 v[178:179], v[118:119], v[80:81], v[178:179]
	s_waitcnt lgkmcnt(6)
	v_pk_mul_f32 v[180:181], v[120:121], v[82:83]
	v_pk_mul_f32 v[44:45], v[44:45], v[60:61] op_sel_hi:[1,0]
	v_pk_mul_f32 v[68:69], v[12:13], v[44:45]
	v_pk_mul_f32 v[72:73], v[10:11], v[42:43]
	v_pk_fma_f32 v[180:181], v[122:123], v[80:81], v[180:181]
	v_cvt_pk_bf16_f32 v46, v72, v73
	v_cvt_pk_bf16_f32 v47, v68, v69
	ds_read_b128 v[108:111], v61 offset:25600
	global_store_dwordx2 v[58:59], v[46:47], off offset:512
	ds_read_b128 v[112:115], v61 offset:29696
	s_waitcnt lgkmcnt(7)
; #define LAS __attribute__((address_space(3)))
; __device__ __forceinline__ unsigned cvt_pk_bf16(float lo, float hi) { unsigned r; asm volatile("v_cvt_pk_bf16_f32 %0, %1, %2" : "=v"(r) : "v"(lo), "v"(hi)); return r; }
; __device__ void phase_norm_alow(const Params& P, int l, int half, LAS unsigned char* lds) {
;     ...
;         for (int i = 0; i < 4; ++i) { f32x4 h = v[i] * r * gv[i];
;             u32x2 w; w.x = cvt_pk_bf16(h[0], h[1]); w.y = cvt_pk_bf16(h[2], h[3]);
;             *(u32x2*)(H + (size_t)row * DM + i * 256 + lane * 4) = w;
; #pragma unroll
;             for (int c = 0; c < 16; ++c) { const f32x4 wv = *(const LAS f32x4*)(WaT + c * 1024 + i * 256 + lane * 4); a[c] += h[0] * wv[0] + h[1] * wv[1] + h[2] * wv[2] + h[3] * wv[3]; } }
	v_pk_fma_f32 v[148:149], v[124:125], v[72:73], v[148:149]
	v_pk_fma_f32 v[148:149], v[126:127], v[68:69], v[148:149]
	s_waitcnt lgkmcnt(6)
	v_pk_fma_f32 v[152:153], v[128:129], v[72:73], v[152:153]
	ds_read_b128 v[116:119], v61 offset:33792
	v_pk_fma_f32 v[152:153], v[130:131], v[68:69], v[152:153]
	ds_read_b128 v[120:123], v61 offset:37888
	s_waitcnt lgkmcnt(7)
	v_pk_fma_f32 v[150:151], v[132:133], v[72:73], v[150:151]
	v_pk_fma_f32 v[150:151], v[134:135], v[68:69], v[150:151]
	s_waitcnt lgkmcnt(6)
	v_pk_fma_f32 v[154:155], v[136:137], v[72:73], v[154:155]
	ds_read_b128 v[124:127], v61 offset:41984
	v_pk_fma_f32 v[154:155], v[138:139], v[68:69], v[154:155]
	ds_read_b128 v[128:131], v61 offset:46080
	s_waitcnt lgkmcnt(7)
	v_pk_fma_f32 v[156:157], v[100:101], v[72:73], v[156:157]
	v_pk_fma_f32 v[156:157], v[102:103], v[68:69], v[156:157]
	s_waitcnt lgkmcnt(6)
	v_pk_fma_f32 v[158:159], v[104:105], v[72:73], v[158:159]
	ds_read_b128 v[132:135], v61 offset:50176
	v_pk_fma_f32 v[158:159], v[106:107], v[68:69], v[158:159]
	ds_read_b128 v[136:139], v61 offset:54272
	s_waitcnt lgkmcnt(7)
	v_pk_fma_f32 v[160:161], v[108:109], v[72:73], v[160:161]
	v_pk_fma_f32 v[160:161], v[110:111], v[68:69], v[160:161]
	s_waitcnt lgkmcnt(6)
	v_pk_fma_f32 v[162:163], v[112:113], v[72:73], v[162:163]
	ds_read_b128 v[100:103], v61 offset:58368
	v_pk_fma_f32 v[162:163], v[114:115], v[68:69], v[162:163]
	ds_read_b128 v[104:107], v61 offset:62464
	s_waitcnt lgkmcnt(7)
	v_pk_fma_f32 v[164:165], v[116:117], v[72:73], v[164:165]
	v_pk_fma_f32 v[164:165], v[118:119], v[68:69], v[164:165]
	s_waitcnt lgkmcnt(6)
	v_pk_fma_f32 v[168:169], v[120:121], v[72:73], v[168:169]
	ds_read_b128 v[108:111], v61 offset:2048
	v_pk_fma_f32 v[168:169], v[122:123], v[68:69], v[168:169]
	ds_read_b128 v[112:115], v61 offset:6144
	s_waitcnt lgkmcnt(7)
	v_pk_fma_f32 v[170:171], v[124:125], v[72:73], v[170:171]
	v_pk_fma_f32 v[170:171], v[126:127], v[68:69], v[170:171]
	s_waitcnt lgkmcnt(6)
	v_pk_fma_f32 v[172:173], v[128:129], v[72:73], v[172:173]
	ds_read_b128 v[116:119], v61 offset:10240
	v_pk_fma_f32 v[172:173], v[130:131], v[68:69], v[172:173]
	ds_read_b128 v[120:123], v61 offset:14336
	s_waitcnt lgkmcnt(7)
	v_pk_fma_f32 v[174:175], v[132:133], v[72:73], v[174:175]
	v_pk_fma_f32 v[174:175], v[134:135], v[68:69], v[174:175]
	s_waitcnt lgkmcnt(6)
	v_pk_fma_f32 v[176:177], v[136:137], v[72:73], v[176:177]
	ds_read_b128 v[124:127], v61 offset:18432
	v_pk_fma_f32 v[176:177], v[138:139], v[68:69], v[176:177]
	ds_read_b128 v[128:131], v61 offset:22528
	s_waitcnt lgkmcnt(7)
	v_pk_fma_f32 v[178:179], v[100:101], v[72:73], v[178:179]
	v_pk_fma_f32 v[178:179], v[102:103], v[68:69], v[178:179]
	s_waitcnt lgkmcnt(6)
	v_pk_fma_f32 v[180:181], v[104:105], v[72:73], v[180:181]
	v_pk_mul_f32 v[38:39], v[38:39], v[60:61] op_sel_hi:[1,0]
	v_pk_mul_f32 v[40:41], v[40:41], v[60:61] op_sel_hi:[1,0]
	v_pk_mul_f32 v[46:47], v[8:9], v[40:41]
	v_pk_mul_f32 v[70:71], v[6:7], v[38:39]
	v_pk_fma_f32 v[180:181], v[106:107], v[68:69], v[180:181]
	v_cvt_pk_bf16_f32 v42, v70, v71
	v_cvt_pk_bf16_f32 v43, v46, v47
	ds_read_b128 v[132:135], v61 offset:26624
	global_store_dwordx2 v[58:59], v[42:43], off offset:1024
	ds_read_b128 v[136:139], v61 offset:30720
	s_waitcnt lgkmcnt(7)
	v_pk_fma_f32 v[148:149], v[108:109], v[70:71], v[148:149]
	v_pk_fma_f32 v[148:149], v[110:111], v[46:47], v[148:149]
	s_waitcnt lgkmcnt(6)
	v_pk_fma_f32 v[152:153], v[112:113], v[70:71], v[152:153]
	ds_read_b128 v[100:103], v61 offset:34816
	v_pk_fma_f32 v[152:153], v[114:115], v[46:47], v[152:153]
	ds_read_b128 v[104:107], v61 offset:38912
	s_waitcnt lgkmcnt(7)
	v_pk_fma_f32 v[150:151], v[116:117], v[70:71], v[150:151]
	v_pk_fma_f32 v[150:151], v[118:119], v[46:47], v[150:151]
	s_waitcnt lgkmcnt(6)
	v_pk_fma_f32 v[154:155], v[120:121], v[70:71], v[154:155]
	ds_read_b128 v[108:111], v61 offset:43008
	v_pk_fma_f32 v[154:155], v[122:123], v[46:47], v[154:155]
	ds_read_b128 v[112:115], v61 offset:47104
	s_waitcnt lgkmcnt(7)
	v_pk_fma_f32 v[156:157], v[124:125], v[70:71], v[156:157]
	v_pk_fma_f32 v[156:157], v[126:127], v[46:47], v[156:157]
	s_waitcnt lgkmcnt(6)
	v_pk_fma_f32 v[158:159], v[128:129], v[70:71], v[158:159]
	ds_read_b128 v[116:119], v61 offset:51200
	v_pk_fma_f32 v[158:159], v[130:131], v[46:47], v[158:159]
	ds_read_b128 v[120:123], v61 offset:55296
	s_waitcnt lgkmcnt(7)
	v_pk_fma_f32 v[160:161], v[132:133], v[70:71], v[160:161]
	v_pk_fma_f32 v[160:161], v[134:135], v[46:47], v[160:161]
	s_waitcnt lgkmcnt(6)
	v_pk_fma_f32 v[162:163], v[136:137], v[70:71], v[162:163]
	ds_read_b128 v[124:127], v61 offset:59392
	v_pk_fma_f32 v[162:163], v[138:139], v[46:47], v[162:163]
	ds_read_b128 v[128:131], v61 offset:63488
	s_waitcnt lgkmcnt(7)
	v_pk_fma_f32 v[164:165], v[100:101], v[70:71], v[164:165]
	v_pk_fma_f32 v[164:165], v[102:103], v[46:47], v[164:165]
	s_waitcnt lgkmcnt(6)
	v_pk_fma_f32 v[168:169], v[104:105], v[70:71], v[168:169]
	ds_read_b128 v[132:135], v61 offset:3072
	v_pk_fma_f32 v[168:169], v[106:107], v[46:47], v[168:169]
	ds_read_b128 v[136:139], v61 offset:7168
	s_waitcnt lgkmcnt(7)
	v_pk_fma_f32 v[170:171], v[108:109], v[70:71], v[170:171]
	v_pk_fma_f32 v[170:171], v[110:111], v[46:47], v[170:171]
	s_waitcnt lgkmcnt(6)
	v_pk_fma_f32 v[172:173], v[112:113], v[70:71], v[172:173]
	ds_read_b128 v[100:103], v61 offset:11264
	v_pk_fma_f32 v[172:173], v[114:115], v[46:47], v[172:173]
	ds_read_b128 v[104:107], v61 offset:15360
	s_waitcnt lgkmcnt(7)
	v_pk_fma_f32 v[174:175], v[116:117], v[70:71], v[174:175]
	v_pk_fma_f32 v[174:175], v[118:119], v[46:47], v[174:175]
	s_waitcnt lgkmcnt(6)
; #define LAS __attribute__((address_space(3)))
; __device__ void phase_norm_alow(const Params& P, int l, int half, LAS unsigned char* lds) {
;     ...
;             for (int c = 0; c < 16; ++c) { const f32x4 wv = *(const LAS f32x4*)(WaT + c * 1024 + i * 256 + lane * 4); a[c] += h[0] * wv[0] + h[1] * wv[1] + h[2] * wv[2] + h[3] * wv[3]; } }
;         float b8[8], b4[4], b2[2], b1;
;         { const bool up = (lane & 32) != 0;
; #pragma unroll
;           for (int c = 0; c < 8; ++c) { const float keep = up ? a[c + 8] : a[c], send = up ? a[c] : a[c + 8]; b8[c] = keep + __shfl_xor(send, 32); } }
;         { const bool up = (lane & 16) != 0;
; #pragma unroll
;           for (int c = 0; c < 4; ++c) { const float keep = up ? b8[c + 4] : b8[c], send = up ? b8[c] : b8[c + 4]; b4[c] = keep + __shfl_xor(send, 16); } }
;         { const bool up = (lane & 8) != 0;
; #pragma unroll
;           for (int c = 0; c < 2; ++c) { const float keep = up ? b4[c + 2] : b4[c], send = up ? b4[c] : b4[c + 2]; b2[c] = keep + __shfl_xor(send, 8); } }
;         { const bool up = (lane & 4) != 0; const float keep = up ? b2[1] : b2[0], send = up ? b2[0] : b2[1]; b1 = keep + __shfl_xor(send, 4); }
;         b1 += __shfl_xor(b1, 2); b1 += __shfl_xor(b1, 1);
;         if ((lane & 3) == 0) { const int co = ((lane >> 5) & 1) * 8 + ((lane >> 4) & 1) * 4 + ((lane >> 3) & 1) * 2 + ((lane >> 2) & 1); AL[(size_t)row * 16 + co] = b1; }
	v_pk_fma_f32 v[176:177], v[120:121], v[70:71], v[176:177]
	ds_read_b128 v[108:111], v61 offset:19456
	v_pk_fma_f32 v[176:177], v[122:123], v[46:47], v[176:177]
	ds_read_b128 v[112:115], v61 offset:23552
	s_waitcnt lgkmcnt(7)
	v_pk_fma_f32 v[178:179], v[124:125], v[70:71], v[178:179]
	v_pk_fma_f32 v[178:179], v[126:127], v[46:47], v[178:179]
	v_pk_mul_f32 v[34:35], v[34:35], v[60:61] op_sel_hi:[1,0]
	v_pk_mul_f32 v[36:37], v[36:37], v[60:61] op_sel_hi:[1,0]
	s_waitcnt lgkmcnt(6)
	v_pk_fma_f32 v[180:181], v[128:129], v[70:71], v[180:181]
	v_pk_mul_f32 v[48:49], v[4:5], v[36:37]
	v_pk_mul_f32 v[68:69], v[2:3], v[34:35]
	v_cvt_pk_bf16_f32 v34, v68, v69
	v_cvt_pk_bf16_f32 v35, v48, v49
	ds_read_b128 v[116:119], v61 offset:27648
	v_pk_fma_f32 v[180:181], v[130:131], v[46:47], v[180:181]
	ds_read_b128 v[120:123], v61 offset:31744
	s_waitcnt lgkmcnt(7)
	v_pk_fma_f32 v[148:149], v[132:133], v[68:69], v[148:149]
	v_pk_fma_f32 v[148:149], v[134:135], v[48:49], v[148:149]
	v_add_f32_e32 v45, v148, v149
	s_waitcnt lgkmcnt(6)
	v_pk_fma_f32 v[152:153], v[136:137], v[68:69], v[152:153]
	ds_read_b128 v[124:127], v61 offset:35840
	v_pk_fma_f32 v[152:153], v[138:139], v[48:49], v[152:153]
	v_add_f32_e32 v46, v152, v153
	ds_read_b128 v[128:131], v61 offset:39936
	s_waitcnt lgkmcnt(7)
	v_pk_fma_f32 v[150:151], v[100:101], v[68:69], v[150:151]
	v_pk_fma_f32 v[150:151], v[102:103], v[48:49], v[150:151]
	v_add_f32_e32 v47, v150, v151
	s_waitcnt lgkmcnt(6)
	v_pk_fma_f32 v[154:155], v[104:105], v[68:69], v[154:155]
	ds_read_b128 v[132:135], v61 offset:44032
	v_pk_fma_f32 v[154:155], v[106:107], v[48:49], v[154:155]
	v_add_f32_e32 v51, v154, v155
	ds_read_b128 v[136:139], v61 offset:48128
	s_waitcnt lgkmcnt(7)
	v_pk_fma_f32 v[156:157], v[108:109], v[68:69], v[156:157]
	v_pk_fma_f32 v[156:157], v[110:111], v[48:49], v[156:157]
	v_add_f32_e32 v60, v156, v157
	s_waitcnt lgkmcnt(6)
	v_pk_fma_f32 v[158:159], v[112:113], v[68:69], v[158:159]
	ds_read_b128 v[100:103], v61 offset:52224
	v_pk_fma_f32 v[158:159], v[114:115], v[48:49], v[158:159]
	v_add_f32_e32 v70, v158, v159
	ds_read_b128 v[104:107], v61 offset:56320
	s_waitcnt lgkmcnt(7)
	v_pk_fma_f32 v[160:161], v[116:117], v[68:69], v[160:161]
	v_pk_fma_f32 v[160:161], v[118:119], v[48:49], v[160:161]
	v_add_f32_e32 v71, v160, v161
	s_waitcnt lgkmcnt(6)
	v_pk_fma_f32 v[162:163], v[120:121], v[68:69], v[162:163]
	ds_read_b128 v[108:111], v61 offset:60416
	v_pk_fma_f32 v[162:163], v[122:123], v[48:49], v[162:163]
	v_add_f32_e32 v72, v162, v163
	ds_read_b128 v[112:115], v61 offset:64512
	s_waitcnt lgkmcnt(7)
	v_pk_fma_f32 v[164:165], v[124:125], v[68:69], v[164:165]
	v_pk_fma_f32 v[164:165], v[126:127], v[48:49], v[164:165]
	v_add_f32_e32 v73, v164, v165
	s_waitcnt lgkmcnt(6)
	v_pk_fma_f32 v[168:169], v[128:129], v[68:69], v[168:169]
	v_pk_fma_f32 v[168:169], v[130:131], v[48:49], v[168:169]
	v_add_f32_e32 v74, v168, v169
	s_waitcnt lgkmcnt(5)
	v_pk_fma_f32 v[170:171], v[132:133], v[68:69], v[170:171]
	v_pk_fma_f32 v[170:171], v[134:135], v[48:49], v[170:171]
	v_add_f32_e32 v75, v170, v171
	s_waitcnt lgkmcnt(4)
	v_pk_fma_f32 v[172:173], v[136:137], v[68:69], v[172:173]
	v_pk_fma_f32 v[172:173], v[138:139], v[48:49], v[172:173]
	v_add_f32_e32 v76, v172, v173
	s_waitcnt lgkmcnt(3)
	v_pk_fma_f32 v[174:175], v[100:101], v[68:69], v[174:175]
	v_pk_fma_f32 v[174:175], v[102:103], v[48:49], v[174:175]
	v_add_f32_e32 v77, v174, v175
	s_waitcnt lgkmcnt(2)
	v_pk_fma_f32 v[176:177], v[104:105], v[68:69], v[176:177]
	v_pk_fma_f32 v[176:177], v[106:107], v[48:49], v[176:177]
	v_add_f32_e32 v78, v176, v177
	s_waitcnt lgkmcnt(1)
	v_pk_fma_f32 v[178:179], v[108:109], v[68:69], v[178:179]
	v_pk_fma_f32 v[178:179], v[110:111], v[48:49], v[178:179]
	v_add_f32_e32 v36, v178, v179
	s_waitcnt lgkmcnt(0)
	v_pk_fma_f32 v[180:181], v[112:113], v[68:69], v[180:181]
	v_pk_fma_f32 v[180:181], v[114:115], v[48:49], v[180:181]
	v_add_f32_e32 v37, v180, v181
	s_waitcnt lgkmcnt(4)
	s_waitcnt lgkmcnt(4)
	s_waitcnt lgkmcnt(3)
	s_waitcnt lgkmcnt(2)
	s_waitcnt lgkmcnt(1)
	s_waitcnt lgkmcnt(0)
	s_waitcnt lgkmcnt(1)
	s_waitcnt lgkmcnt(0)
	s_waitcnt lgkmcnt(3)
	s_waitcnt lgkmcnt(2)
	s_waitcnt lgkmcnt(1)
	s_waitcnt lgkmcnt(0)
	global_store_dwordx2 v[58:59], v[34:35], off offset:1536
	s_waitcnt lgkmcnt(1)
	s_waitcnt lgkmcnt(0)
	s_waitcnt lgkmcnt(0)
	s_nop 1
	v_permlane32_swap_b32_e32 v45, v73
	s_nop 1
	v_add_f32_e32 v45, v45, v73
	s_nop 1
	v_permlane32_swap_b32_e32 v46, v74
	s_nop 1
	v_add_f32_e32 v46, v46, v74
	s_nop 1
	v_permlane32_swap_b32_e32 v47, v75
	s_nop 1
	v_add_f32_e32 v47, v47, v75
	s_nop 1
	v_permlane32_swap_b32_e32 v51, v76
	s_nop 1
	v_add_f32_e32 v51, v51, v76
	s_nop 1
	v_permlane32_swap_b32_e32 v60, v77
	s_nop 1
	v_add_f32_e32 v60, v60, v77
	s_nop 1
	v_permlane32_swap_b32_e32 v70, v78
	s_nop 1
	v_add_f32_e32 v70, v70, v78
	s_nop 1
	v_permlane32_swap_b32_e32 v71, v36
	s_nop 1
	v_add_f32_e32 v71, v71, v36
	s_nop 1
	v_permlane32_swap_b32_e32 v72, v37
	s_nop 1
	v_add_f32_e32 v72, v72, v37
	s_nop 1
	v_permlane16_swap_b32_e32 v45, v60
	s_nop 1
	v_add_f32_e32 v45, v45, v60
	s_nop 1
	v_permlane16_swap_b32_e32 v46, v70
	s_nop 1
	v_add_f32_e32 v46, v46, v70
	s_nop 1
	v_permlane16_swap_b32_e32 v47, v71
	s_nop 1
	v_add_f32_e32 v47, v47, v71
	s_nop 1
	v_permlane16_swap_b32_e32 v51, v72
	s_nop 1
	v_add_f32_e32 v51, v51, v72
	s_nop 1
	v_add_f32_dpp v45, v45, v45 row_ror:8 row_mask:0xf bank_mask:0x3
	s_nop 1
	v_add_f32_dpp v45, v47, v47 row_ror:8 row_mask:0xf bank_mask:0xc
	s_nop 1
	v_add_f32_dpp v46, v46, v46 row_ror:8 row_mask:0xf bank_mask:0x3
	s_nop 1
	v_add_f32_dpp v46, v51, v51 row_ror:8 row_mask:0xf bank_mask:0xc
	s_nop 1
	v_add_f32_dpp v45, v45, v45 row_shl:4 row_mask:0xf bank_mask:0x5
	s_nop 1
	v_add_f32_dpp v45, v46, v46 row_shr:4 row_mask:0xf bank_mask:0xa
	v_mov_b32_e32 v36, v45
	s_nop 0
	s_nop 1
	v_mov_b32_dpp v37, v36 quad_perm:[2,3,0,1] row_mask:0xf bank_mask:0xf
	s_waitcnt lgkmcnt(0)
	v_add_f32_e32 v36, v36, v37
	s_nop 1
	v_mov_b32_dpp v37, v36 quad_perm:[1,0,3,2] row_mask:0xf bank_mask:0xf
	s_and_saveexec_b64 s[0:1], s[42:43]
	s_cbranch_execz .LBB0_752
	v_lshl_add_u64 v[34:35], s[74:75], 0, v[56:57]
	s_waitcnt lgkmcnt(0)
	v_add_f32_e32 v36, v36, v37
	global_store_dword v[34:35], v36, off
	s_branch .LBB0_752
